# MLA loops: QK-first schedule, next-tile max in tail gaps, 4-slot LDS ring with counted vmcnt (loads issued 2 steps ahead)
# speedup vs baseline: 1.0003x; 1.0003x over previous
; template <bool SWA> ...
;     ...
;     AT_GLOAD(0, 0); AT_GLOAD(1, AT_BUF);
;     asm volatile("s_waitcnt vmcnt(0)" ::: "memory");
;     __syncthreads();
;     f32x16 o0, o1, negm;
;     float mref = SWA ? m_init : 0.f, lrun = l_init;
; #pragma unroll
;     for (int r = 0; r < 16; ++r) { o0[r] = 0.f; o1[r] = 0.f; negm[r] = -mref; }
.LBB0_1008:
	s_lshr_b32 s6, s12, 5
	s_and_b32 s6, s6, 7
	s_lshl_b32 s15, s6, 7
	s_lshl_b32 s19, s6, 22
	s_lshl_b64 s[6:7], s[4:5], 23
	v_add_u32_e32 v6, s18, v236
	s_lshl_b32 s13, s13, 6
	v_lshl_or_b32 v206, v6, 1, s6
	s_or_b32 s6, s6, s15
	s_lshl_b64 s[4:5], s[4:5], 14
	s_add_u32 s4, s19, s4
	v_mov_b32_e32 v6, s6
	v_mov_b32_e32 v7, s7
	s_addc_u32 s5, 0, s5
	v_mov_b32_e32 v16, v1
	v_mov_b32_e32 v17, v1
	v_lshl_add_u64 v[208:209], v[4:5], 1, v[6:7]
	v_lshl_add_u64 v[210:211], v[2:3], 1, s[4:5]
	v_mov_b32_e32 v2, v1
	v_mov_b32_e32 v3, v1
	v_mov_b32_e32 v4, v1
	v_mov_b32_e32 v5, v1
	v_mov_b32_e32 v6, v1
	v_mov_b32_e32 v7, v1
	v_mov_b32_e32 v8, v1
	v_mov_b32_e32 v9, v1
	v_mov_b32_e32 v10, v1
	v_mov_b32_e32 v11, v1
	v_mov_b32_e32 v12, v1
	v_mov_b32_e32 v13, v1
	v_mov_b32_e32 v14, v1
	v_mov_b32_e32 v15, v1
	v_bfrev_b32_e32 v82, 1
	v_mov_b64_e32 v[32:33], v[16:17]
	v_readlane_b32 s36, v254, 54
	v_mov_b32_e32 v207, s7
	s_mov_b32 s4, 0
	s_mov_b32 s18, 0xa000
	s_movk_i32 s15, 0x5000
	v_mov_b32_e32 v239, 0
	s_mov_b32 s19, -2
	v_mov_b64_e32 v[30:31], v[14:15]
	v_mov_b64_e32 v[28:29], v[12:13]
	v_mov_b64_e32 v[26:27], v[10:11]
	v_mov_b64_e32 v[24:25], v[8:9]
	v_mov_b64_e32 v[22:23], v[6:7]
	v_mov_b64_e32 v[20:21], v[4:5]
	v_mov_b64_e32 v[18:19], v[2:3]
	v_mov_b32_e32 v170, 0
	v_mov_b32_e32 v83, v82
	v_mov_b32_e32 v84, v82
	v_mov_b32_e32 v85, v82
	v_mov_b32_e32 v86, v82
	v_mov_b32_e32 v87, v82
	v_mov_b32_e32 v88, v82
	v_mov_b32_e32 v89, v82
	v_mov_b32_e32 v90, v82
	v_mov_b32_e32 v91, v82
	v_mov_b32_e32 v92, v82
	v_mov_b32_e32 v93, v82
	v_mov_b32_e32 v94, v82
	v_mov_b32_e32 v95, v82
	v_mov_b32_e32 v96, v82
	v_mov_b32_e32 v97, v82
	v_readlane_b32 s38, v254, 56
	v_readlane_b32 s39, v254, 57
	v_readlane_b32 s37, v254, 55
	s_mov_b32 s20, 0xf000
	v_lshl_add_u64 v[154:155], s[38:39], 0, v[208:209]
	v_lshl_add_u64 v[156:157], s[38:39], 0, v[210:211]
	v_lshl_add_u64 v[158:159], s[38:39], 0, v[206:207]
	s_mov_b64 s[6:7], 0x17020000
	s_add_i32 s24, s14, s18
	v_lshl_add_u64 v[218:219], v[154:155], 0, s[6:7]
	s_mov_b32 m0, s24
	s_mov_b64 s[6:7], 0x18008100
	global_load_lds_dwordx4 v[218:219], off
	v_lshl_add_u64 v[218:219], v[156:157], 0, s[6:7]
	s_add_i32 m0, s24, 0x3000
	s_andn2_b64 vcc, exec, s[16:17]
	global_load_lds_dwordx4 v[218:219], off
	s_cbranch_vccnz .LmlaLP_nokr
	s_mov_b64 s[6:7], 0x8820300
	v_lshl_add_u64 v[218:219], v[158:159], 0, s[6:7]
	s_add_i32 m0, s24, 0x2000
	s_nop 0
	global_load_lds_dwordx4 v[218:219], off
.LmlaLP_nokr:
	v_max3_f32 v162, v66, v67, v68
	v_max3_f32 v163, v50, v51, v52
	v_max3_f32 v162, v162, v69, v70
	v_max3_f32 v163, v163, v53, v54
	v_max3_f32 v162, v162, v71, v72
	v_max3_f32 v163, v163, v55, v56
	v_max3_f32 v162, v162, v73, v74
	v_max3_f32 v163, v163, v57, v58
	v_max3_f32 v162, v162, v75, v76
	v_max3_f32 v163, v163, v59, v60
	v_max3_f32 v162, v162, v77, v78
	v_max3_f32 v163, v163, v61, v62
	v_max3_f32 v162, v162, v79, v80
	v_max3_f32 v163, v163, v63, v64
	v_max3_f32 v162, v162, v81, v65
	v_max_f32_e32 v162, v162, v163
.LmlaL_top:
	v_add_u32_e32 v164, s15, v238
	v_add_u32_e32 v165, s4, v238
	ds_read_b128 v[172:175], v164
	ds_read_b128 v[176:179], v164 offset:512
	ds_read_b128 v[180:183], v164 offset:2048
	ds_read_b128 v[184:187], v164 offset:2560
	ds_read_b128 v[188:191], v164 offset:4096
	v_lshl_add_u64 v[154:155], s[38:39], 0, v[208:209]
	v_lshl_add_u64 v[156:157], s[38:39], 0, v[210:211]
	v_lshl_add_u64 v[158:159], s[38:39], 0, v[206:207]
	s_mov_b64 s[6:7], 0x17030000
	s_add_i32 s24, s14, s20
	v_lshl_add_u64 v[218:219], v[154:155], 0, s[6:7]
	s_mov_b32 m0, s24
	s_mov_b64 s[6:7], 0x18008180
	global_load_lds_dwordx4 v[218:219], off
	v_lshl_add_u64 v[218:219], v[156:157], 0, s[6:7]
	s_add_i32 m0, s24, 0x3000
	s_andn2_b64 vcc, exec, s[16:17]
	global_load_lds_dwordx4 v[218:219], off
	s_cbranch_vccnz .LmlaLA_nokr
	s_mov_b64 s[6:7], 0x8830300
	v_lshl_add_u64 v[218:219], v[158:159], 0, s[6:7]
	s_add_i32 m0, s24, 0x2000
	s_nop 0
	global_load_lds_dwordx4 v[218:219], off
.LmlaLA_nokr:
	s_cmp_eq_u32 s19, -2
	s_cselect_b64 s[6:7], -1, 0
	v_cmp_lt_f32_e32 vcc, s33, v162
	s_or_b64 vcc, s[6:7], vcc
	s_cbranch_vccz .LmlaLA_common
	v_mov_b32_e32 v163, v162
	s_nop 1
	v_permlane32_swap_b32_e32 v162, v163
	v_max_f32_e32 v162, v162, v163
	v_max_f32_e32 v220, 0, v162
	v_cndmask_b32_e64 v220, v220, v162, s[6:7]
	v_exp_f32_e64 v222, -v220
	v_add_f32_e32 v239, v239, v220
	v_pk_add_f32 v[66:67], v[66:67], v[220:221] op_sel_hi:[1,0] neg_lo:[0,1] neg_hi:[0,1]
	v_pk_add_f32 v[68:69], v[68:69], v[220:221] op_sel_hi:[1,0] neg_lo:[0,1] neg_hi:[0,1]
	v_pk_add_f32 v[70:71], v[70:71], v[220:221] op_sel_hi:[1,0] neg_lo:[0,1] neg_hi:[0,1]
	v_pk_add_f32 v[72:73], v[72:73], v[220:221] op_sel_hi:[1,0] neg_lo:[0,1] neg_hi:[0,1]
	v_pk_add_f32 v[74:75], v[74:75], v[220:221] op_sel_hi:[1,0] neg_lo:[0,1] neg_hi:[0,1]
	v_pk_add_f32 v[76:77], v[76:77], v[220:221] op_sel_hi:[1,0] neg_lo:[0,1] neg_hi:[0,1]
	v_pk_add_f32 v[78:79], v[78:79], v[220:221] op_sel_hi:[1,0] neg_lo:[0,1] neg_hi:[0,1]
	v_pk_add_f32 v[80:81], v[80:81], v[220:221] op_sel_hi:[1,0] neg_lo:[0,1] neg_hi:[0,1]
	v_pk_add_f32 v[50:51], v[50:51], v[220:221] op_sel_hi:[1,0] neg_lo:[0,1] neg_hi:[0,1]
	v_pk_add_f32 v[52:53], v[52:53], v[220:221] op_sel_hi:[1,0] neg_lo:[0,1] neg_hi:[0,1]
	v_pk_add_f32 v[54:55], v[54:55], v[220:221] op_sel_hi:[1,0] neg_lo:[0,1] neg_hi:[0,1]
	v_pk_add_f32 v[56:57], v[56:57], v[220:221] op_sel_hi:[1,0] neg_lo:[0,1] neg_hi:[0,1]
	v_pk_add_f32 v[58:59], v[58:59], v[220:221] op_sel_hi:[1,0] neg_lo:[0,1] neg_hi:[0,1]
	v_pk_add_f32 v[60:61], v[60:61], v[220:221] op_sel_hi:[1,0] neg_lo:[0,1] neg_hi:[0,1]
	v_pk_add_f32 v[62:63], v[62:63], v[220:221] op_sel_hi:[1,0] neg_lo:[0,1] neg_hi:[0,1]
	v_pk_add_f32 v[64:65], v[64:65], v[220:221] op_sel_hi:[1,0] neg_lo:[0,1] neg_hi:[0,1]
	v_pk_mul_f32 v[2:3], v[2:3], v[222:223] op_sel_hi:[1,0]
	v_pk_mul_f32 v[4:5], v[4:5], v[222:223] op_sel_hi:[1,0]
	v_pk_mul_f32 v[6:7], v[6:7], v[222:223] op_sel_hi:[1,0]
	v_pk_mul_f32 v[8:9], v[8:9], v[222:223] op_sel_hi:[1,0]
	v_pk_mul_f32 v[10:11], v[10:11], v[222:223] op_sel_hi:[1,0]
	v_pk_mul_f32 v[12:13], v[12:13], v[222:223] op_sel_hi:[1,0]
	v_pk_mul_f32 v[14:15], v[14:15], v[222:223] op_sel_hi:[1,0]
	v_pk_mul_f32 v[16:17], v[16:17], v[222:223] op_sel_hi:[1,0]
	v_pk_mul_f32 v[18:19], v[18:19], v[222:223] op_sel_hi:[1,0]
	v_pk_mul_f32 v[20:21], v[20:21], v[222:223] op_sel_hi:[1,0]
	v_pk_mul_f32 v[22:23], v[22:23], v[222:223] op_sel_hi:[1,0]
	v_pk_mul_f32 v[24:25], v[24:25], v[222:223] op_sel_hi:[1,0]
	v_pk_mul_f32 v[26:27], v[26:27], v[222:223] op_sel_hi:[1,0]
	v_pk_mul_f32 v[28:29], v[28:29], v[222:223] op_sel_hi:[1,0]
	v_pk_mul_f32 v[30:31], v[30:31], v[222:223] op_sel_hi:[1,0]
	v_pk_mul_f32 v[32:33], v[32:33], v[222:223] op_sel_hi:[1,0]
	v_mul_f32_e32 v170, v170, v222
	v_xor_b32_e32 v82, 0x80000000, v239
	v_mov_b32_e32 v83, v82
	v_mov_b32_e32 v84, v82
	v_mov_b32_e32 v85, v82
	v_mov_b32_e32 v86, v82
	v_mov_b32_e32 v87, v82
	v_mov_b32_e32 v88, v82
	v_mov_b32_e32 v89, v82
	v_mov_b32_e32 v90, v82
	v_mov_b32_e32 v91, v82
	v_mov_b32_e32 v92, v82
	v_mov_b32_e32 v93, v82
	v_mov_b32_e32 v94, v82
	v_mov_b32_e32 v95, v82
	v_mov_b32_e32 v96, v82
	v_mov_b32_e32 v97, v82
	s_nop 1
.LmlaLA_common:
	s_waitcnt lgkmcnt(4)
	v_mfma_f32_32x32x16_bf16 v[98:113], v[172:175], v[150:153], v[82:97]
	ds_read_b128 v[192:195], v164 offset:4608
	v_exp_f32_e32 v66, v66
	v_exp_f32_e32 v67, v67
	v_exp_f32_e32 v68, v68
	s_waitcnt lgkmcnt(4)
	v_mfma_f32_32x32x16_bf16 v[114:129], v[176:179], v[150:153], v[82:97]
	ds_read_b128 v[240:243], v164 offset:6144
	v_exp_f32_e32 v69, v69
	v_exp_f32_e32 v70, v70
	v_exp_f32_e32 v71, v71
	s_waitcnt lgkmcnt(4)
	v_mfma_f32_32x32x16_bf16 v[98:113], v[180:183], v[134:137], v[98:113]
	ds_read_b128 v[244:247], v164 offset:6656
	v_exp_f32_e32 v72, v72
	v_exp_f32_e32 v73, v73
	v_cvt_pk_bf16_f32 v34, v66, v67
	v_cvt_pk_bf16_f32 v35, v68, v69
	s_waitcnt lgkmcnt(4)
	v_mfma_f32_32x32x16_bf16 v[114:129], v[184:187], v[134:137], v[114:129]
	ds_read_b128 v[248:251], v164 offset:8192
	v_exp_f32_e32 v74, v74
	v_exp_f32_e32 v75, v75
	v_cvt_pk_bf16_f32 v36, v70, v71
	v_cvt_pk_bf16_f32 v37, v72, v73
	s_waitcnt lgkmcnt(4)
	v_mfma_f32_32x32x16_bf16 v[98:113], v[188:191], v[138:141], v[98:113]
	ds_read_b128 v[172:175], v164 offset:8704
	v_exp_f32_e32 v76, v76
	v_exp_f32_e32 v77, v77
	v_exp_f32_e32 v78, v78
	s_waitcnt lgkmcnt(4)
	v_mfma_f32_32x32x16_bf16 v[114:129], v[192:195], v[138:141], v[114:129]
	ds_read_b128 v[176:179], v164 offset:10240
	v_exp_f32_e32 v79, v79
	v_exp_f32_e32 v80, v80
	v_exp_f32_e32 v81, v81
	s_waitcnt lgkmcnt(4)
	v_mfma_f32_32x32x16_bf16 v[98:113], v[240:243], v[142:145], v[98:113]
	ds_read_b128 v[180:183], v164 offset:10752
	v_exp_f32_e32 v50, v50
	v_exp_f32_e32 v51, v51
	v_cvt_pk_bf16_f32 v38, v74, v75
	v_cvt_pk_bf16_f32 v39, v76, v77
	s_waitcnt lgkmcnt(4)
	v_mfma_f32_32x32x16_bf16 v[114:129], v[244:247], v[142:145], v[114:129]
	ds_read_b128 v[184:187], v165 offset:12288
	v_exp_f32_e32 v52, v52
	v_exp_f32_e32 v53, v53
	v_cvt_pk_bf16_f32 v40, v78, v79
	v_cvt_pk_bf16_f32 v41, v80, v81
	s_waitcnt lgkmcnt(4)
	v_mfma_f32_32x32x16_bf16 v[98:113], v[248:251], v[146:149], v[98:113]
	ds_read_b128 v[188:191], v165 offset:12800
	v_exp_f32_e32 v54, v54
	v_exp_f32_e32 v55, v55
	v_exp_f32_e32 v56, v56
	s_waitcnt lgkmcnt(4)
	v_mfma_f32_32x32x16_bf16 v[114:129], v[172:175], v[146:149], v[114:129]
	ds_read_b128 v[192:195], v165 offset:14336
	v_exp_f32_e32 v57, v57
	v_exp_f32_e32 v58, v58
	v_cvt_pk_bf16_f32 v42, v50, v51
	v_cvt_pk_bf16_f32 v43, v52, v53
	s_waitcnt lgkmcnt(4)
	v_mfma_f32_32x32x16_bf16 v[98:113], v[176:179], v[130:133], v[98:113]
	ds_read_b128 v[240:243], v165 offset:14848
	v_exp_f32_e32 v59, v59
	v_exp_f32_e32 v60, v60
	v_cvt_pk_bf16_f32 v44, v54, v55
	v_cvt_pk_bf16_f32 v45, v56, v57
	s_waitcnt lgkmcnt(4)
	v_mfma_f32_32x32x16_bf16 v[114:129], v[180:183], v[130:133], v[114:129]
	ds_read_b128 v[244:247], v165 offset:16384
	v_exp_f32_e32 v61, v61
	v_exp_f32_e32 v62, v62
	v_exp_f32_e32 v63, v63
	s_waitcnt lgkmcnt(4)
	v_mfma_f32_32x32x16_bf16 v[2:17], v[184:187], v[34:37], v[2:17]
	ds_read_b128 v[248:251], v165 offset:16896
	v_exp_f32_e32 v64, v64
	v_exp_f32_e32 v65, v65
	v_cvt_pk_bf16_f32 v46, v58, v59
	v_cvt_pk_bf16_f32 v47, v60, v61
	s_waitcnt lgkmcnt(4)
	v_mfma_f32_32x32x16_bf16 v[18:33], v[188:191], v[34:37], v[18:33]
	ds_read_b128 v[172:175], v165 offset:18432
	v_cvt_pk_bf16_f32 v48, v62, v63
	v_cvt_pk_bf16_f32 v49, v64, v65
	v_add_f32_e32 v166, v66, v67
	v_add_f32_e32 v167, v68, v69
	v_add_f32_e32 v168, v70, v71
	v_add_f32_e32 v169, v72, v73
	s_waitcnt lgkmcnt(4)
	v_mfma_f32_32x32x16_bf16 v[2:17], v[192:195], v[38:41], v[2:17]
	ds_read_b128 v[176:179], v165 offset:18944
	v_add_f32_e32 v166, v166, v74
	v_add_f32_e32 v167, v167, v75
	v_add_f32_e32 v168, v168, v76
	v_add_f32_e32 v169, v169, v77
	v_max3_f32 v162, v98, v99, v100
	v_max3_f32 v163, v114, v115, v116
	s_waitcnt lgkmcnt(4)
	v_mfma_f32_32x32x16_bf16 v[18:33], v[240:243], v[38:41], v[18:33]
	v_add_f32_e32 v166, v166, v78
	v_add_f32_e32 v167, v167, v79
	v_add_f32_e32 v168, v168, v80
	v_add_f32_e32 v169, v169, v81
	v_max3_f32 v162, v162, v101, v102
	v_max3_f32 v163, v163, v117, v118
	s_waitcnt lgkmcnt(3)
	v_mfma_f32_32x32x16_bf16 v[2:17], v[244:247], v[42:45], v[2:17]
	v_add_f32_e32 v166, v166, v50
	v_add_f32_e32 v167, v167, v51
	v_add_f32_e32 v168, v168, v52
	v_add_f32_e32 v169, v169, v53
	v_max3_f32 v162, v162, v103, v104
	v_max3_f32 v163, v163, v119, v120
	s_waitcnt lgkmcnt(2)
	v_mfma_f32_32x32x16_bf16 v[18:33], v[248:251], v[42:45], v[18:33]
	v_add_f32_e32 v166, v166, v54
	v_add_f32_e32 v167, v167, v55
	v_add_f32_e32 v168, v168, v56
	v_add_f32_e32 v169, v169, v57
	v_max3_f32 v162, v162, v105, v106
	v_max3_f32 v163, v163, v121, v122
	s_waitcnt lgkmcnt(1)
	v_mfma_f32_32x32x16_bf16 v[2:17], v[172:175], v[46:49], v[2:17]
	v_add_f32_e32 v166, v166, v58
	v_add_f32_e32 v167, v167, v59
	v_add_f32_e32 v168, v168, v60
	v_add_f32_e32 v169, v169, v61
	v_max3_f32 v162, v162, v107, v108
	v_max3_f32 v163, v163, v123, v124
	s_waitcnt lgkmcnt(0)
	v_mfma_f32_32x32x16_bf16 v[18:33], v[176:179], v[46:49], v[18:33]
	v_add_f32_e32 v166, v166, v62
	v_add_f32_e32 v167, v167, v63
	v_add_f32_e32 v168, v168, v64
	v_add_f32_e32 v169, v169, v65
	v_max3_f32 v162, v162, v109, v110
	v_max3_f32 v163, v163, v125, v126
	v_max3_f32 v162, v162, v111, v112
	v_max3_f32 v163, v163, v127, v128
	v_add_f32_e32 v166, v166, v167
	v_add_f32_e32 v168, v168, v169
	v_add_f32_e32 v166, v166, v168
	v_add_f32_e32 v170, v170, v166
	v_max3_f32 v162, v162, v113, v129
	v_max_f32_e32 v162, v162, v163
	s_andn2_b64 vcc, exec, s[16:17]
	s_cbranch_vccnz .LmlaLA_w2
	s_waitcnt vmcnt(3)
	s_branch .LmlaLA_wd
.LmlaLA_w2:
	s_waitcnt vmcnt(2)
.LmlaLA_wd:
	s_barrier
	v_add_u32_e32 v164, s18, v238
	v_add_u32_e32 v165, s15, v238
	ds_read_b128 v[172:175], v164
	ds_read_b128 v[176:179], v164 offset:512
	ds_read_b128 v[180:183], v164 offset:2048
	ds_read_b128 v[184:187], v164 offset:2560
	ds_read_b128 v[188:191], v164 offset:4096
	s_mov_b64 s[6:7], 0x17040000
	s_add_i32 s24, s14, s4
	v_lshl_add_u64 v[218:219], v[154:155], 0, s[6:7]
	s_mov_b32 m0, s24
	s_mov_b64 s[6:7], 0x18008200
	global_load_lds_dwordx4 v[218:219], off
	v_lshl_add_u64 v[218:219], v[156:157], 0, s[6:7]
	s_add_i32 m0, s24, 0x3000
	s_andn2_b64 vcc, exec, s[16:17]
	global_load_lds_dwordx4 v[218:219], off
	s_cbranch_vccnz .LmlaLB_nokr
	s_mov_b64 s[6:7], 0x8840300
	v_lshl_add_u64 v[218:219], v[158:159], 0, s[6:7]
	s_add_i32 m0, s24, 0x2000
	s_nop 0
	global_load_lds_dwordx4 v[218:219], off
.LmlaLB_nokr:
	v_cmp_lt_f32_e32 vcc, s33, v162
	s_cbranch_vccz .LmlaLB_common
	v_mov_b32_e32 v163, v162
	s_nop 1
	v_permlane32_swap_b32_e32 v162, v163
	v_max_f32_e32 v162, v162, v163
	v_max_f32_e32 v220, 0, v162
	v_exp_f32_e64 v222, -v220
	v_add_f32_e32 v239, v239, v220
	v_pk_add_f32 v[98:99], v[98:99], v[220:221] op_sel_hi:[1,0] neg_lo:[0,1] neg_hi:[0,1]
	v_pk_add_f32 v[100:101], v[100:101], v[220:221] op_sel_hi:[1,0] neg_lo:[0,1] neg_hi:[0,1]
	v_pk_add_f32 v[102:103], v[102:103], v[220:221] op_sel_hi:[1,0] neg_lo:[0,1] neg_hi:[0,1]
	v_pk_add_f32 v[104:105], v[104:105], v[220:221] op_sel_hi:[1,0] neg_lo:[0,1] neg_hi:[0,1]
	v_pk_add_f32 v[106:107], v[106:107], v[220:221] op_sel_hi:[1,0] neg_lo:[0,1] neg_hi:[0,1]
	v_pk_add_f32 v[108:109], v[108:109], v[220:221] op_sel_hi:[1,0] neg_lo:[0,1] neg_hi:[0,1]
	v_pk_add_f32 v[110:111], v[110:111], v[220:221] op_sel_hi:[1,0] neg_lo:[0,1] neg_hi:[0,1]
	v_pk_add_f32 v[112:113], v[112:113], v[220:221] op_sel_hi:[1,0] neg_lo:[0,1] neg_hi:[0,1]
	v_pk_add_f32 v[114:115], v[114:115], v[220:221] op_sel_hi:[1,0] neg_lo:[0,1] neg_hi:[0,1]
	v_pk_add_f32 v[116:117], v[116:117], v[220:221] op_sel_hi:[1,0] neg_lo:[0,1] neg_hi:[0,1]
	v_pk_add_f32 v[118:119], v[118:119], v[220:221] op_sel_hi:[1,0] neg_lo:[0,1] neg_hi:[0,1]
	v_pk_add_f32 v[120:121], v[120:121], v[220:221] op_sel_hi:[1,0] neg_lo:[0,1] neg_hi:[0,1]
	v_pk_add_f32 v[122:123], v[122:123], v[220:221] op_sel_hi:[1,0] neg_lo:[0,1] neg_hi:[0,1]
	v_pk_add_f32 v[124:125], v[124:125], v[220:221] op_sel_hi:[1,0] neg_lo:[0,1] neg_hi:[0,1]
	v_pk_add_f32 v[126:127], v[126:127], v[220:221] op_sel_hi:[1,0] neg_lo:[0,1] neg_hi:[0,1]
	v_pk_add_f32 v[128:129], v[128:129], v[220:221] op_sel_hi:[1,0] neg_lo:[0,1] neg_hi:[0,1]
	v_pk_mul_f32 v[2:3], v[2:3], v[222:223] op_sel_hi:[1,0]
	v_pk_mul_f32 v[4:5], v[4:5], v[222:223] op_sel_hi:[1,0]
	v_pk_mul_f32 v[6:7], v[6:7], v[222:223] op_sel_hi:[1,0]
	v_pk_mul_f32 v[8:9], v[8:9], v[222:223] op_sel_hi:[1,0]
	v_pk_mul_f32 v[10:11], v[10:11], v[222:223] op_sel_hi:[1,0]
	v_pk_mul_f32 v[12:13], v[12:13], v[222:223] op_sel_hi:[1,0]
	v_pk_mul_f32 v[14:15], v[14:15], v[222:223] op_sel_hi:[1,0]
	v_pk_mul_f32 v[16:17], v[16:17], v[222:223] op_sel_hi:[1,0]
	v_pk_mul_f32 v[18:19], v[18:19], v[222:223] op_sel_hi:[1,0]
	v_pk_mul_f32 v[20:21], v[20:21], v[222:223] op_sel_hi:[1,0]
	v_pk_mul_f32 v[22:23], v[22:23], v[222:223] op_sel_hi:[1,0]
	v_pk_mul_f32 v[24:25], v[24:25], v[222:223] op_sel_hi:[1,0]
	v_pk_mul_f32 v[26:27], v[26:27], v[222:223] op_sel_hi:[1,0]
	v_pk_mul_f32 v[28:29], v[28:29], v[222:223] op_sel_hi:[1,0]
	v_pk_mul_f32 v[30:31], v[30:31], v[222:223] op_sel_hi:[1,0]
	v_pk_mul_f32 v[32:33], v[32:33], v[222:223] op_sel_hi:[1,0]
	v_mul_f32_e32 v170, v170, v222
	v_xor_b32_e32 v82, 0x80000000, v239
	v_mov_b32_e32 v83, v82
	v_mov_b32_e32 v84, v82
	v_mov_b32_e32 v85, v82
	v_mov_b32_e32 v86, v82
	v_mov_b32_e32 v87, v82
	v_mov_b32_e32 v88, v82
	v_mov_b32_e32 v89, v82
	v_mov_b32_e32 v90, v82
	v_mov_b32_e32 v91, v82
	v_mov_b32_e32 v92, v82
	v_mov_b32_e32 v93, v82
	v_mov_b32_e32 v94, v82
	v_mov_b32_e32 v95, v82
	v_mov_b32_e32 v96, v82
	v_mov_b32_e32 v97, v82
	s_nop 1
; template <bool SWA> ...
;     ...
;     int t = 0;
;     if (wv >= 4) __builtin_amdgcn_s_setprio(1);
;     for (; t < ntiles - 2; t += 2) { AT_STEP(t, sA0, sA1, sB0, sB1, true); AT_STEP(t + 1, sB0, sB1, sA0, sA1, true); }
.LmlaLB_common:
	s_waitcnt lgkmcnt(4)
	v_mfma_f32_32x32x16_bf16 v[66:81], v[172:175], v[150:153], v[82:97]
	ds_read_b128 v[192:195], v164 offset:4608
	v_exp_f32_e32 v98, v98
	v_exp_f32_e32 v99, v99
	v_exp_f32_e32 v100, v100
	s_waitcnt lgkmcnt(4)
	v_mfma_f32_32x32x16_bf16 v[50:65], v[176:179], v[150:153], v[82:97]
	ds_read_b128 v[240:243], v164 offset:6144
	v_exp_f32_e32 v101, v101
	v_exp_f32_e32 v102, v102
	v_exp_f32_e32 v103, v103
	s_waitcnt lgkmcnt(4)
	v_mfma_f32_32x32x16_bf16 v[66:81], v[180:183], v[134:137], v[66:81]
	ds_read_b128 v[244:247], v164 offset:6656
	v_exp_f32_e32 v104, v104
	v_exp_f32_e32 v105, v105
	v_cvt_pk_bf16_f32 v34, v98, v99
	v_cvt_pk_bf16_f32 v35, v100, v101
	s_waitcnt lgkmcnt(4)
	v_mfma_f32_32x32x16_bf16 v[50:65], v[184:187], v[134:137], v[50:65]
	ds_read_b128 v[248:251], v164 offset:8192
	v_exp_f32_e32 v106, v106
	v_exp_f32_e32 v107, v107
	v_cvt_pk_bf16_f32 v36, v102, v103
	v_cvt_pk_bf16_f32 v37, v104, v105
	s_waitcnt lgkmcnt(4)
	v_mfma_f32_32x32x16_bf16 v[66:81], v[188:191], v[138:141], v[66:81]
	ds_read_b128 v[172:175], v164 offset:8704
	v_exp_f32_e32 v108, v108
	v_exp_f32_e32 v109, v109
	v_exp_f32_e32 v110, v110
	s_waitcnt lgkmcnt(4)
	v_mfma_f32_32x32x16_bf16 v[50:65], v[192:195], v[138:141], v[50:65]
	ds_read_b128 v[176:179], v164 offset:10240
	v_exp_f32_e32 v111, v111
	v_exp_f32_e32 v112, v112
	v_exp_f32_e32 v113, v113
	s_waitcnt lgkmcnt(4)
	v_mfma_f32_32x32x16_bf16 v[66:81], v[240:243], v[142:145], v[66:81]
	ds_read_b128 v[180:183], v164 offset:10752
	v_exp_f32_e32 v114, v114
	v_exp_f32_e32 v115, v115
	v_cvt_pk_bf16_f32 v38, v106, v107
	v_cvt_pk_bf16_f32 v39, v108, v109
	s_waitcnt lgkmcnt(4)
	v_mfma_f32_32x32x16_bf16 v[50:65], v[244:247], v[142:145], v[50:65]
	ds_read_b128 v[184:187], v165 offset:12288
	v_exp_f32_e32 v116, v116
	v_exp_f32_e32 v117, v117
	v_cvt_pk_bf16_f32 v40, v110, v111
	v_cvt_pk_bf16_f32 v41, v112, v113
	s_waitcnt lgkmcnt(4)
	v_mfma_f32_32x32x16_bf16 v[66:81], v[248:251], v[146:149], v[66:81]
	ds_read_b128 v[188:191], v165 offset:12800
	v_exp_f32_e32 v118, v118
	v_exp_f32_e32 v119, v119
	v_exp_f32_e32 v120, v120
	s_waitcnt lgkmcnt(4)
	v_mfma_f32_32x32x16_bf16 v[50:65], v[172:175], v[146:149], v[50:65]
	ds_read_b128 v[192:195], v165 offset:14336
	v_exp_f32_e32 v121, v121
	v_exp_f32_e32 v122, v122
	v_cvt_pk_bf16_f32 v42, v114, v115
	v_cvt_pk_bf16_f32 v43, v116, v117
	s_waitcnt lgkmcnt(4)
	v_mfma_f32_32x32x16_bf16 v[66:81], v[176:179], v[130:133], v[66:81]
	ds_read_b128 v[240:243], v165 offset:14848
	v_exp_f32_e32 v123, v123
	v_exp_f32_e32 v124, v124
	v_cvt_pk_bf16_f32 v44, v118, v119
	v_cvt_pk_bf16_f32 v45, v120, v121
	s_waitcnt lgkmcnt(4)
	v_mfma_f32_32x32x16_bf16 v[50:65], v[180:183], v[130:133], v[50:65]
	ds_read_b128 v[244:247], v165 offset:16384
	v_exp_f32_e32 v125, v125
	v_exp_f32_e32 v126, v126
	v_exp_f32_e32 v127, v127
	s_waitcnt lgkmcnt(4)
	v_mfma_f32_32x32x16_bf16 v[2:17], v[184:187], v[34:37], v[2:17]
	ds_read_b128 v[248:251], v165 offset:16896
	v_exp_f32_e32 v128, v128
	v_exp_f32_e32 v129, v129
	v_cvt_pk_bf16_f32 v46, v122, v123
	v_cvt_pk_bf16_f32 v47, v124, v125
	s_waitcnt lgkmcnt(4)
	v_mfma_f32_32x32x16_bf16 v[18:33], v[188:191], v[34:37], v[18:33]
	ds_read_b128 v[172:175], v165 offset:18432
	v_cvt_pk_bf16_f32 v48, v126, v127
	v_cvt_pk_bf16_f32 v49, v128, v129
	v_add_f32_e32 v166, v98, v99
	v_add_f32_e32 v167, v100, v101
	v_add_f32_e32 v168, v102, v103
	v_add_f32_e32 v169, v104, v105
	s_waitcnt lgkmcnt(4)
	v_mfma_f32_32x32x16_bf16 v[2:17], v[192:195], v[38:41], v[2:17]
	ds_read_b128 v[176:179], v165 offset:18944
	v_add_f32_e32 v166, v166, v106
	v_add_f32_e32 v167, v167, v107
	v_add_f32_e32 v168, v168, v108
	v_add_f32_e32 v169, v169, v109
	v_max3_f32 v162, v66, v67, v68
	v_max3_f32 v163, v50, v51, v52
	s_waitcnt lgkmcnt(4)
	v_mfma_f32_32x32x16_bf16 v[18:33], v[240:243], v[38:41], v[18:33]
	v_add_f32_e32 v166, v166, v110
	v_add_f32_e32 v167, v167, v111
	v_add_f32_e32 v168, v168, v112
	v_add_f32_e32 v169, v169, v113
	v_max3_f32 v162, v162, v69, v70
	v_max3_f32 v163, v163, v53, v54
	s_waitcnt lgkmcnt(3)
	v_mfma_f32_32x32x16_bf16 v[2:17], v[244:247], v[42:45], v[2:17]
	v_add_f32_e32 v166, v166, v114
	v_add_f32_e32 v167, v167, v115
	v_add_f32_e32 v168, v168, v116
	v_add_f32_e32 v169, v169, v117
	v_max3_f32 v162, v162, v71, v72
	v_max3_f32 v163, v163, v55, v56
	s_waitcnt lgkmcnt(2)
	v_mfma_f32_32x32x16_bf16 v[18:33], v[248:251], v[42:45], v[18:33]
	v_add_f32_e32 v166, v166, v118
	v_add_f32_e32 v167, v167, v119
	v_add_f32_e32 v168, v168, v120
	v_add_f32_e32 v169, v169, v121
	v_max3_f32 v162, v162, v73, v74
	v_max3_f32 v163, v163, v57, v58
	s_waitcnt lgkmcnt(1)
	v_mfma_f32_32x32x16_bf16 v[2:17], v[172:175], v[46:49], v[2:17]
	v_add_f32_e32 v166, v166, v122
	v_add_f32_e32 v167, v167, v123
	v_add_f32_e32 v168, v168, v124
	v_add_f32_e32 v169, v169, v125
	v_max3_f32 v162, v162, v75, v76
	v_max3_f32 v163, v163, v59, v60
	s_waitcnt lgkmcnt(0)
	v_mfma_f32_32x32x16_bf16 v[18:33], v[176:179], v[46:49], v[18:33]
	v_add_f32_e32 v166, v166, v126
	v_add_f32_e32 v167, v167, v127
	v_add_f32_e32 v168, v168, v128
	v_add_f32_e32 v169, v169, v129
	v_max3_f32 v162, v162, v77, v78
	v_max3_f32 v163, v163, v61, v62
	v_max3_f32 v162, v162, v79, v80
	v_max3_f32 v163, v163, v63, v64
	v_add_f32_e32 v166, v166, v167
	v_add_f32_e32 v168, v168, v169
	v_add_f32_e32 v166, v166, v168
	v_add_f32_e32 v170, v170, v166
	v_max3_f32 v162, v162, v81, v65
	v_max_f32_e32 v162, v162, v163
	s_add_i32 s19, s19, 2
	v_lshl_add_u64 v[206:207], v[206:207], 0, s[34:35]
	v_lshl_add_u64 v[208:209], v[208:209], 0, s[34:35]
	v_lshl_add_u64 v[210:211], v[210:211], 0, s[28:29]
	s_andn2_b64 vcc, exec, s[16:17]
	s_cbranch_vccnz .LmlaLB_w2
	s_waitcnt vmcnt(3)
	s_branch .LmlaLB_wd

; template <bool SWA> ...
;     ...
;     int t = 0;
;     if (wv >= 4) __builtin_amdgcn_s_setprio(1);
;     for (; t < ntiles - 2; t += 2) { AT_STEP(t, sA0, sA1, sB0, sB1, true); AT_STEP(t + 1, sB0, sB1, sA0, sA1, true); }
;     AT_STEP(t, sA0, sA1, sB0, sB1, true);
;     AT_STEP(t + 1, sB0, sB1, sA0, sA1, false);
.LmlaLB_wd:
	s_barrier
	s_cmpk_lt_u32 s19, 0x7c
	s_cbranch_scc0 .LmlaL_exit
	s_mov_b32 s5, s4
	s_mov_b32 s4, s18
	s_mov_b32 s18, s5
	s_mov_b32 s5, s15
	s_mov_b32 s15, s20
	s_mov_b32 s20, s5
	s_branch .LmlaL_top
.LmlaL_exit:
	v_add_u32_e32 v171, 0xa000, v238
	v_mov_b64_e32 v[34:35], v[82:83]
	v_mov_b64_e32 v[36:37], v[84:85]
	v_mov_b64_e32 v[38:39], v[86:87]
	v_mov_b64_e32 v[40:41], v[88:89]
	v_mov_b64_e32 v[42:43], v[90:91]
	v_mov_b64_e32 v[44:45], v[92:93]
	v_mov_b64_e32 v[46:47], v[94:95]
	v_mov_b64_e32 v[48:49], v[96:97]

; template <bool SWA> ...
;     ...
;     int t = 0;
;     if (wv >= 4) __builtin_amdgcn_s_setprio(1);
;     for (; t < ntiles - 2; t += 2) { AT_STEP(t, sA0, sA1, sB0, sB1, true); AT_STEP(t + 1, sB0, sB1, sA0, sA1, true); }
;     AT_STEP(t, sA0, sA1, sB0, sB1, true);
.LBB0_1022:
	ds_read_b128 v[98:101], v171 offset:20480
	ds_read_b128 v[102:105], v171 offset:22528
	ds_read_b128 v[106:109], v171 offset:24576
	ds_read_b128 v[110:113], v171 offset:26624
	s_waitcnt lgkmcnt(3)
	v_mfma_f32_32x32x16_bf16 v[82:97], v[98:101], v[150:153], v[34:49]
	ds_read_b128 v[98:101], v171 offset:20992
	ds_read_b128 v[114:117], v171 offset:28672
	v_exp_f32_e32 v66, v66
	v_exp_f32_e32 v50, v50
	v_exp_f32_e32 v52, v52
	v_exp_f32_e32 v124, v69
	s_waitcnt lgkmcnt(1)
	v_mfma_f32_32x32x16_bf16 v[34:49], v[98:101], v[150:153], v[34:49]
	ds_read_b128 v[98:101], v171 offset:23040
	ds_read_b128 v[118:121], v171 offset:31232
	v_exp_f32_e32 v122, v53
	v_exp_f32_e32 v53, v70
	v_exp_f32_e32 v128, v71
	v_exp_f32_e32 v126, v55
	s_waitcnt lgkmcnt(1)
	v_mfma_f32_32x32x16_bf16 v[34:49], v[98:101], v[134:137], v[34:49]
	ds_read_b128 v[98:101], v171 offset:25088
	v_exp_f32_e32 v152, v73
	v_exp_f32_e32 v150, v57
	v_exp_f32_e32 v55, v74
	v_exp_f32_e32 v69, v58
	s_waitcnt lgkmcnt(0)
	v_mfma_f32_32x32x16_bf16 v[34:49], v[98:101], v[138:141], v[34:49]
	ds_read_b128 v[98:101], v171 offset:27136
	v_add_f32_e32 v155, v69, v55
	v_exp_f32_e32 v156, v75
	v_exp_f32_e32 v154, v59
	v_exp_f32_e32 v70, v60
	s_waitcnt lgkmcnt(0)
	v_mfma_f32_32x32x16_bf16 v[34:49], v[98:101], v[142:145], v[34:49]
	ds_read_b128 v[98:101], v171 offset:29184
	v_exp_f32_e32 v160, v77
	v_exp_f32_e32 v158, v61
	v_exp_f32_e32 v57, v78
	v_exp_f32_e32 v71, v62
	s_waitcnt lgkmcnt(0)
	v_mfma_f32_32x32x16_bf16 v[34:49], v[98:101], v[146:149], v[34:49]
	ds_read_b128 v[98:101], v171 offset:30720
	v_add_f32_e32 v163, v71, v57
	v_exp_f32_e32 v164, v79
	v_exp_f32_e32 v162, v63
	v_exp_f32_e32 v73, v64
	v_mfma_f32_32x32x16_bf16 v[34:49], v[118:121], v[130:133], v[34:49]
	v_add_f32_e32 v119, v50, v66
	v_exp_f32_e32 v120, v67
	v_exp_f32_e32 v118, v51
	v_exp_f32_e32 v51, v68
	v_mfma_f32_32x32x16_bf16 v[82:97], v[102:105], v[134:137], v[82:97]
	ds_read_b128 v[102:105], v171 offset:18432
	v_exp_f32_e32 v67, v54
	v_add_f32_e32 v123, v52, v51
	v_exp_f32_e32 v54, v72
	v_add_f32_e32 v127, v67, v53
	v_mfma_f32_32x32x16_bf16 v[82:97], v[106:109], v[138:141], v[82:97]
	ds_read_b128 v[106:109], v171 offset:16384
	v_exp_f32_e32 v68, v56
	v_exp_f32_e32 v56, v76
	v_add_f32_e32 v151, v68, v54
	v_add_f32_e32 v159, v70, v56
	v_mfma_f32_32x32x16_bf16 v[82:97], v[110:113], v[142:145], v[82:97]
	ds_read_b128 v[110:113], v171 offset:14336
	ds_read_b128 v[74:77], v171 offset:14848
	v_exp_f32_e32 v72, v80
	v_exp_f32_e32 v168, v81
	v_exp_f32_e32 v166, v65
	v_add_f32_e32 v167, v73, v72
	v_mfma_f32_32x32x16_bf16 v[82:97], v[114:117], v[146:149], v[82:97]
	ds_read_b128 v[114:117], v171 offset:12288
	ds_read_b128 v[78:81], v171 offset:16896
	v_cvt_pk_bf16_f32 v58, v66, v120
	v_cvt_pk_bf16_f32 v59, v51, v124
	v_cvt_pk_bf16_f32 v60, v53, v128
	v_cvt_pk_bf16_f32 v61, v54, v152
	s_waitcnt lgkmcnt(6)
	v_mfma_f32_32x32x16_bf16 v[82:97], v[98:101], v[130:133], v[82:97]
	v_cvt_pk_bf16_f32 v63, v56, v160
	v_cvt_pk_bf16_f32 v64, v57, v164
	v_cvt_pk_bf16_f32 v54, v50, v118
	v_cvt_pk_bf16_f32 v56, v67, v126
	v_cvt_pk_bf16_f32 v57, v68, v150
	v_cvt_pk_bf16_f32 v50, v69, v154
	ds_read_b128 v[66:69], v171 offset:18944
	v_cvt_pk_bf16_f32 v62, v55, v156
	v_cvt_pk_bf16_f32 v65, v72, v168
	v_cvt_pk_bf16_f32 v55, v52, v122
	v_cvt_pk_bf16_f32 v51, v70, v158
	v_cvt_pk_bf16_f32 v52, v71, v162
	v_cvt_pk_bf16_f32 v53, v73, v166
	ds_read_b128 v[70:73], v171 offset:12800
	v_mov_b32_e32 v121, v1
	v_pk_add_f32 v[118:119], v[118:119], v[120:121]
	s_waitcnt lgkmcnt(0)
	v_mfma_f32_32x32x16_bf16 v[18:33], v[70:73], v[58:61], v[18:33]
	v_pk_add_f32 v[118:119], v[118:119], v[118:119] op_sel_hi:[0,1]
	v_mov_b32_e32 v125, v119
	v_mfma_f32_32x32x16_bf16 v[2:17], v[114:117], v[58:61], v[2:17]
	v_add_f32_e64 v118, v122, v124
	v_add_f32_e64 v119, v123, v125
	v_pk_add_f32 v[118:119], v[118:119], v[118:119] op_sel_hi:[0,1]
	v_mov_b32_e32 v129, v119
	v_pk_add_f32 v[118:119], v[126:127], v[128:129]
	s_nop 0
	v_pk_add_f32 v[118:119], v[118:119], v[118:119] op_sel_hi:[0,1]
	v_mov_b32_e32 v153, v119
	v_mfma_f32_32x32x16_bf16 v[2:17], v[110:113], v[62:65], v[2:17]
	v_add_f32_e64 v118, v150, v152
	v_add_f32_e64 v119, v151, v153
	v_pk_add_f32 v[118:119], v[118:119], v[118:119] op_sel_hi:[0,1]
	v_mov_b32_e32 v157, v119
	v_pk_add_f32 v[118:119], v[154:155], v[156:157]
	v_mfma_f32_32x32x16_bf16 v[18:33], v[74:77], v[62:65], v[18:33]
	v_pk_add_f32 v[118:119], v[118:119], v[118:119] op_sel_hi:[0,1]
	v_mov_b32_e32 v161, v119
	v_mfma_f32_32x32x16_bf16 v[2:17], v[106:109], v[54:57], v[2:17]
	v_add_f32_e64 v118, v158, v160
	v_add_f32_e64 v119, v159, v161
	v_pk_add_f32 v[118:119], v[118:119], v[118:119] op_sel_hi:[0,1]
	v_mov_b32_e32 v165, v119
	v_pk_add_f32 v[118:119], v[162:163], v[164:165]
	v_mfma_f32_32x32x16_bf16 v[18:33], v[78:81], v[54:57], v[18:33]
	v_pk_add_f32 v[118:119], v[118:119], v[118:119] op_sel_hi:[0,1]
	v_mov_b32_e32 v169, v119
	v_mfma_f32_32x32x16_bf16 v[2:17], v[102:105], v[50:53], v[2:17]
	v_add_f32_e64 v118, v166, v168
	v_add_f32_e64 v119, v167, v169
	v_add_f32_e32 v98, v118, v119
	v_mfma_f32_32x32x16_bf16 v[18:33], v[66:69], v[50:53], v[18:33]
	v_max_f32_e32 v50, v83, v83
	v_max_f32_e32 v51, v82, v82
	v_max_f32_e32 v50, v51, v50
	v_max3_f32 v51, v84, v85, v35
	v_max3_f32 v50, v50, v34, v36
	v_max3_f32 v50, v50, v37, v86
	v_max3_f32 v51, v51, v88, v89
	v_max3_f32 v50, v50, v87, v38
	v_max3_f32 v51, v51, v40, v41
	v_max3_f32 v50, v50, v39, v90
	v_max3_f32 v51, v51, v92, v93
	v_max3_f32 v50, v50, v91, v42
	v_max3_f32 v51, v51, v44, v45
	v_max3_f32 v50, v50, v43, v94
	v_max3_f32 v51, v51, v96, v97
	v_max3_f32 v50, v50, v95, v46
	v_max3_f32 v51, v51, v48, v49
	v_max3_f32 v50, v50, v47, v51
	v_mov_b32_e32 v51, v50
	s_nop 1
	v_permlane32_swap_b32_e32 v50, v51
	s_waitcnt vmcnt(0)
	v_max_f32_e32 v51, v51, v51
	v_max_f32_e32 v50, v50, v50
	v_max_f32_e32 v50, v50, v51
	v_add_f32_e32 v72, v170, v98
	v_cmp_lt_f32_e32 vcc, s33, v50
	s_barrier
; template <bool SWA> ...
;     ...
;     int t = 0;
;     if (wv >= 4) __builtin_amdgcn_s_setprio(1);
;     for (; t < ntiles - 2; t += 2) { AT_STEP(t, sA0, sA1, sB0, sB1, true); AT_STEP(t + 1, sB0, sB1, sA0, sA1, true); }
;     AT_STEP(t, sA0, sA1, sB0, sB1, true);
	s_cbranch_vccz .LBB0_1024
	v_max_f32_e32 v50, v50, v50
	v_max_f32_e32 v50, 0, v50
	v_exp_f32_e64 v52, -v50
	v_pk_add_f32 v[82:83], v[82:83], v[50:51] op_sel_hi:[1,0] neg_lo:[0,1] neg_hi:[0,1]
	v_pk_add_f32 v[34:35], v[34:35], v[50:51] op_sel_hi:[1,0] neg_lo:[0,1] neg_hi:[0,1]
	v_pk_add_f32 v[84:85], v[84:85], v[50:51] op_sel_hi:[1,0] neg_lo:[0,1] neg_hi:[0,1]
	v_pk_add_f32 v[36:37], v[36:37], v[50:51] op_sel_hi:[1,0] neg_lo:[0,1] neg_hi:[0,1]
	v_pk_add_f32 v[86:87], v[86:87], v[50:51] op_sel_hi:[1,0] neg_lo:[0,1] neg_hi:[0,1]
	v_pk_add_f32 v[38:39], v[38:39], v[50:51] op_sel_hi:[1,0] neg_lo:[0,1] neg_hi:[0,1]
	v_pk_add_f32 v[88:89], v[88:89], v[50:51] op_sel_hi:[1,0] neg_lo:[0,1] neg_hi:[0,1]
	v_pk_add_f32 v[40:41], v[40:41], v[50:51] op_sel_hi:[1,0] neg_lo:[0,1] neg_hi:[0,1]
	v_pk_add_f32 v[90:91], v[90:91], v[50:51] op_sel_hi:[1,0] neg_lo:[0,1] neg_hi:[0,1]
	v_pk_add_f32 v[42:43], v[42:43], v[50:51] op_sel_hi:[1,0] neg_lo:[0,1] neg_hi:[0,1]
	v_pk_add_f32 v[92:93], v[92:93], v[50:51] op_sel_hi:[1,0] neg_lo:[0,1] neg_hi:[0,1]
	v_pk_add_f32 v[44:45], v[44:45], v[50:51] op_sel_hi:[1,0] neg_lo:[0,1] neg_hi:[0,1]
	v_pk_add_f32 v[94:95], v[94:95], v[50:51] op_sel_hi:[1,0] neg_lo:[0,1] neg_hi:[0,1]
	v_pk_add_f32 v[46:47], v[46:47], v[50:51] op_sel_hi:[1,0] neg_lo:[0,1] neg_hi:[0,1]
	v_pk_add_f32 v[96:97], v[96:97], v[50:51] op_sel_hi:[1,0] neg_lo:[0,1] neg_hi:[0,1]
	v_pk_add_f32 v[48:49], v[48:49], v[50:51] op_sel_hi:[1,0] neg_lo:[0,1] neg_hi:[0,1]
	v_pk_mul_f32 v[16:17], v[16:17], v[52:53] op_sel_hi:[1,0]
	v_pk_mul_f32 v[14:15], v[14:15], v[52:53] op_sel_hi:[1,0]
	v_pk_mul_f32 v[12:13], v[12:13], v[52:53] op_sel_hi:[1,0]
	v_pk_mul_f32 v[10:11], v[10:11], v[52:53] op_sel_hi:[1,0]
	v_pk_mul_f32 v[8:9], v[8:9], v[52:53] op_sel_hi:[1,0]
	v_pk_mul_f32 v[6:7], v[6:7], v[52:53] op_sel_hi:[1,0]
	v_pk_mul_f32 v[4:5], v[4:5], v[52:53] op_sel_hi:[1,0]
	v_pk_mul_f32 v[2:3], v[2:3], v[52:53] op_sel_hi:[1,0]
	v_pk_mul_f32 v[32:33], v[32:33], v[52:53] op_sel_hi:[1,0]
	v_pk_mul_f32 v[30:31], v[30:31], v[52:53] op_sel_hi:[1,0]
	v_pk_mul_f32 v[28:29], v[28:29], v[52:53] op_sel_hi:[1,0]
	v_pk_mul_f32 v[26:27], v[26:27], v[52:53] op_sel_hi:[1,0]
	v_pk_mul_f32 v[24:25], v[24:25], v[52:53] op_sel_hi:[1,0]
	v_pk_mul_f32 v[22:23], v[22:23], v[52:53] op_sel_hi:[1,0]
	v_pk_mul_f32 v[20:21], v[20:21], v[52:53] op_sel_hi:[1,0]
	v_pk_mul_f32 v[18:19], v[18:19], v[52:53] op_sel_hi:[1,0]
	v_mul_f32_e32 v72, v72, v52
.LBB0_1024:
	ds_read_b128 v[66:69], v171 offset:32768
	ds_read_b128 v[78:81], v171 offset:33280
	v_exp_f32_e32 v53, v82
	v_exp_f32_e32 v52, v83
	v_exp_f32_e32 v51, v84
	v_exp_f32_e32 v50, v85
	v_exp_f32_e32 v61, v86
	v_exp_f32_e32 v64, v87
	v_exp_f32_e32 v57, v88
	v_exp_f32_e32 v60, v89
	v_cvt_pk_bf16_f32 v74, v53, v52
	v_cvt_pk_bf16_f32 v75, v51, v50
	v_cvt_pk_bf16_f32 v76, v61, v64
	v_cvt_pk_bf16_f32 v77, v57, v60
	v_exp_f32_e32 v63, v90
	v_exp_f32_e32 v62, v91
	s_waitcnt lgkmcnt(1)
	v_mfma_f32_32x32x16_bf16 v[2:17], v[66:69], v[74:77], v[2:17]
	ds_read_b128 v[66:69], v171 offset:34816
	v_exp_f32_e32 v59, v92
	v_exp_f32_e32 v58, v93
	v_exp_f32_e32 v55, v94
	v_exp_f32_e32 v56, v95
	v_exp_f32_e32 v73, v96
	v_exp_f32_e32 v54, v97
	s_waitcnt lgkmcnt(1)
	v_mfma_f32_32x32x16_bf16 v[18:33], v[78:81], v[74:77], v[18:33]
	ds_read_b128 v[78:81], v171 offset:35328
	v_cvt_pk_bf16_f32 v74, v63, v62
	v_cvt_pk_bf16_f32 v75, v59, v58
	v_cvt_pk_bf16_f32 v76, v55, v56
	v_cvt_pk_bf16_f32 v77, v73, v54
	ds_read_b128 v[82:85], v171 offset:36864
	ds_read_b128 v[86:89], v171 offset:37376
	s_waitcnt lgkmcnt(3)
	v_mfma_f32_32x32x16_bf16 v[2:17], v[66:69], v[74:77], v[2:17]
	v_exp_f32_e32 v67, v34
	v_exp_f32_e32 v70, v35
	v_exp_f32_e32 v65, v36
	v_exp_f32_e32 v68, v37
	v_exp_f32_e32 v37, v38
	v_exp_f32_e32 v66, v39
	v_exp_f32_e32 v39, v40
	s_waitcnt lgkmcnt(2)
	v_mfma_f32_32x32x16_bf16 v[18:33], v[78:81], v[74:77], v[18:33]
	v_exp_f32_e32 v40, v41
	v_cvt_pk_bf16_f32 v76, v67, v70
	v_cvt_pk_bf16_f32 v77, v65, v68
	v_cvt_pk_bf16_f32 v78, v37, v66
	v_cvt_pk_bf16_f32 v79, v39, v40
	v_exp_f32_e32 v75, v42
	v_exp_f32_e32 v42, v43
	s_waitcnt lgkmcnt(1)
	v_mfma_f32_32x32x16_bf16 v[2:17], v[82:85], v[76:79], v[2:17]
	ds_read_b128 v[80:83], v171 offset:38912
	v_exp_f32_e32 v74, v44
	v_exp_f32_e32 v38, v45
	v_exp_f32_e32 v35, v46
	v_exp_f32_e32 v36, v47
	v_exp_f32_e32 v44, v48
	v_exp_f32_e32 v34, v49
	s_waitcnt lgkmcnt(1)
	v_mfma_f32_32x32x16_bf16 v[18:33], v[86:89], v[76:79], v[18:33]
	ds_read_b128 v[76:79], v171 offset:39424
	v_cvt_pk_bf16_f32 v46, v75, v42
	v_cvt_pk_bf16_f32 v47, v74, v38
	v_cvt_pk_bf16_f32 v48, v35, v36
	v_cvt_pk_bf16_f32 v49, v44, v34
	s_waitcnt lgkmcnt(1)
	s_nop 0
	v_mfma_f32_32x32x16_bf16 v[2:17], v[80:83], v[46:49], v[2:17]
	s_waitcnt lgkmcnt(0)
	v_mfma_f32_32x32x16_bf16 v[18:33], v[76:79], v[46:49], v[18:33]
	s_waitcnt vmcnt(0)
	s_andn2_b64 vcc, exec, s[10:11]
	s_barrier
	s_cbranch_vccnz .LBB0_1000
	s_setprio 0
	s_branch .LBB0_1000

; template <bool SWA> ...
;     ...
;     AT_GLOAD(0, 0); AT_GLOAD(1, AT_BUF);
;     asm volatile("s_waitcnt vmcnt(0)" ::: "memory");
;     __syncthreads();
;     f32x16 o0, o1, negm;
;     float mref = SWA ? m_init : 0.f, lrun = l_init;
; #pragma unroll
;     for (int r = 0; r < 16; ++r) { o0[r] = 0.f; o1[r] = 0.f; negm[r] = -mref; }
; __global__ void __launch_bounds__(512, 2) mk_fwd(Args a) {
;     ...
;             for (int u = vcu; u < 512; u += G) {
;                 const int bh = u >> 4, qb = u & 15, b = bh >> 3, h = bh & 7; const size_t base = (size_t)b * 4096; const size_t qrow = base + 256 * qb + 32 * wv + l32;
;                 attn_unit<false>(lds, ldsl, Q + qrow * 768 + h * 96, KNOPE + base * 512 + h * 64, 512, LAT + base * 512 + 384, VT + (size_t)(h * 64) * T + base, 64, -1e30f, 0.f, 0, OA + (qrow - l32) * 512 + h * 64, tid);
.LBB0_1034:
	s_lshr_b32 s14, s13, 4
	s_and_b32 s14, s14, 7
	s_lshl_b32 s20, s14, 7
	v_add_u32_e32 v6, s19, v236
	s_lshl_b32 s12, s12, 6
	s_lshl_b32 s14, s14, 22
	v_lshl_or_b32 v206, v6, 1, s4
	s_or_b32 s4, s4, s20
	v_mov_b32_e32 v6, s4
	s_add_u32 s4, s14, s6
	v_mov_b32_e32 v207, s5
	v_mov_b32_e32 v7, s5
	s_addc_u32 s5, 0, s7
	v_mov_b32_e32 v16, v1
	v_mov_b32_e32 v17, v1
	v_lshl_add_u64 v[208:209], v[4:5], 1, v[6:7]
	v_lshl_add_u64 v[210:211], v[2:3], 1, s[4:5]
	v_mov_b32_e32 v2, v1
	v_mov_b32_e32 v3, v1
	v_mov_b32_e32 v4, v1
	v_mov_b32_e32 v5, v1
	v_mov_b32_e32 v6, v1
	v_mov_b32_e32 v7, v1
	v_mov_b32_e32 v8, v1
	v_mov_b32_e32 v9, v1
	v_mov_b32_e32 v10, v1
	v_mov_b32_e32 v11, v1
	v_mov_b32_e32 v12, v1
	v_mov_b32_e32 v13, v1
	v_mov_b32_e32 v14, v1
	v_mov_b32_e32 v15, v1
	v_bfrev_b32_e32 v82, 1
	v_mov_b64_e32 v[32:33], v[16:17]
	v_readlane_b32 s24, v254, 54
	s_mov_b32 s4, 0
	s_mov_b32 s20, 0xa000
	s_movk_i32 s19, 0x5000
	v_mov_b32_e32 v239, 0
	s_mov_b32 s21, -2
	v_mov_b64_e32 v[30:31], v[14:15]
	v_mov_b64_e32 v[28:29], v[12:13]
	v_mov_b64_e32 v[26:27], v[10:11]
	v_mov_b64_e32 v[24:25], v[8:9]
	v_mov_b64_e32 v[22:23], v[6:7]
	v_mov_b64_e32 v[20:21], v[4:5]
	v_mov_b64_e32 v[18:19], v[2:3]
	v_mov_b32_e32 v160, 0
	v_mov_b32_e32 v83, v82
	v_mov_b32_e32 v84, v82
	v_mov_b32_e32 v85, v82
	v_mov_b32_e32 v86, v82
	v_mov_b32_e32 v87, v82
	v_mov_b32_e32 v88, v82
	v_mov_b32_e32 v89, v82
	v_mov_b32_e32 v90, v82
	v_mov_b32_e32 v91, v82
	v_mov_b32_e32 v92, v82
	v_mov_b32_e32 v93, v82
	v_mov_b32_e32 v94, v82
	v_mov_b32_e32 v95, v82
	v_mov_b32_e32 v96, v82
	v_mov_b32_e32 v97, v82
	v_readlane_b32 s26, v254, 56
	v_readlane_b32 s27, v254, 57
	v_readlane_b32 s25, v254, 55
	s_mov_b32 s23, 0xf000
	v_lshl_add_u64 v[154:155], s[26:27], 0, v[208:209]
	v_lshl_add_u64 v[156:157], s[26:27], 0, v[210:211]
	v_lshl_add_u64 v[158:159], s[26:27], 0, v[206:207]
	s_mov_b64 s[6:7], 0x16020000
	s_add_i32 s24, s15, s20
	v_lshl_add_u64 v[218:219], v[154:155], 0, s[6:7]
	s_mov_b32 m0, s24
	s_mov_b64 s[6:7], 0x18000100
	global_load_lds_dwordx4 v[218:219], off
	v_lshl_add_u64 v[218:219], v[156:157], 0, s[6:7]
	s_add_i32 m0, s24, 0x3000
	s_andn2_b64 vcc, exec, s[16:17]
	global_load_lds_dwordx4 v[218:219], off
	s_cbranch_vccnz .LmlaSP_nokr
	s_mov_b64 s[6:7], 0x7820300
	v_lshl_add_u64 v[218:219], v[158:159], 0, s[6:7]
	s_add_i32 m0, s24, 0x2000
	s_nop 0
	global_load_lds_dwordx4 v[218:219], off

.LmlaS_top:
	v_add_u32_e32 v164, s19, v238
	v_add_u32_e32 v165, s4, v238
	ds_read_b128 v[172:175], v164
	ds_read_b128 v[176:179], v164 offset:512
	ds_read_b128 v[180:183], v164 offset:2048
	ds_read_b128 v[184:187], v164 offset:2560
	ds_read_b128 v[188:191], v164 offset:4096
	v_lshl_add_u64 v[154:155], s[26:27], 0, v[208:209]
	v_lshl_add_u64 v[156:157], s[26:27], 0, v[210:211]
	v_lshl_add_u64 v[158:159], s[26:27], 0, v[206:207]
	s_mov_b64 s[6:7], 0x16030000
	s_add_i32 s24, s15, s23
	v_lshl_add_u64 v[218:219], v[154:155], 0, s[6:7]
	s_mov_b32 m0, s24
	s_mov_b64 s[6:7], 0x18000180
	global_load_lds_dwordx4 v[218:219], off
	v_lshl_add_u64 v[218:219], v[156:157], 0, s[6:7]
	s_add_i32 m0, s24, 0x3000
	s_andn2_b64 vcc, exec, s[16:17]
	global_load_lds_dwordx4 v[218:219], off
	s_cbranch_vccnz .LmlaSA_nokr
	s_mov_b64 s[6:7], 0x7830300
	v_lshl_add_u64 v[218:219], v[158:159], 0, s[6:7]
	s_add_i32 m0, s24, 0x2000
	s_nop 0
	global_load_lds_dwordx4 v[218:219], off
.LmlaSA_nokr:
	s_cmp_eq_u32 s21, -2
	s_cselect_b64 s[6:7], -1, 0
	v_cmp_lt_f32_e32 vcc, s33, v162
	s_or_b64 vcc, s[6:7], vcc
	s_cbranch_vccz .LmlaSA_common
	v_mov_b32_e32 v163, v162
	s_nop 1
	v_permlane32_swap_b32_e32 v162, v163
	v_max_f32_e32 v162, v162, v163
	v_max_f32_e32 v220, 0, v162
	v_cndmask_b32_e64 v220, v220, v162, s[6:7]
	v_exp_f32_e64 v222, -v220
	v_add_f32_e32 v239, v239, v220
	v_pk_add_f32 v[66:67], v[66:67], v[220:221] op_sel_hi:[1,0] neg_lo:[0,1] neg_hi:[0,1]
	v_pk_add_f32 v[68:69], v[68:69], v[220:221] op_sel_hi:[1,0] neg_lo:[0,1] neg_hi:[0,1]
	v_pk_add_f32 v[70:71], v[70:71], v[220:221] op_sel_hi:[1,0] neg_lo:[0,1] neg_hi:[0,1]
	v_pk_add_f32 v[72:73], v[72:73], v[220:221] op_sel_hi:[1,0] neg_lo:[0,1] neg_hi:[0,1]
	v_pk_add_f32 v[74:75], v[74:75], v[220:221] op_sel_hi:[1,0] neg_lo:[0,1] neg_hi:[0,1]
	v_pk_add_f32 v[76:77], v[76:77], v[220:221] op_sel_hi:[1,0] neg_lo:[0,1] neg_hi:[0,1]
	v_pk_add_f32 v[78:79], v[78:79], v[220:221] op_sel_hi:[1,0] neg_lo:[0,1] neg_hi:[0,1]
	v_pk_add_f32 v[80:81], v[80:81], v[220:221] op_sel_hi:[1,0] neg_lo:[0,1] neg_hi:[0,1]
	v_pk_add_f32 v[50:51], v[50:51], v[220:221] op_sel_hi:[1,0] neg_lo:[0,1] neg_hi:[0,1]
	v_pk_add_f32 v[52:53], v[52:53], v[220:221] op_sel_hi:[1,0] neg_lo:[0,1] neg_hi:[0,1]
	v_pk_add_f32 v[54:55], v[54:55], v[220:221] op_sel_hi:[1,0] neg_lo:[0,1] neg_hi:[0,1]
	v_pk_add_f32 v[56:57], v[56:57], v[220:221] op_sel_hi:[1,0] neg_lo:[0,1] neg_hi:[0,1]
	v_pk_add_f32 v[58:59], v[58:59], v[220:221] op_sel_hi:[1,0] neg_lo:[0,1] neg_hi:[0,1]
	v_pk_add_f32 v[60:61], v[60:61], v[220:221] op_sel_hi:[1,0] neg_lo:[0,1] neg_hi:[0,1]
	v_pk_add_f32 v[62:63], v[62:63], v[220:221] op_sel_hi:[1,0] neg_lo:[0,1] neg_hi:[0,1]
	v_pk_add_f32 v[64:65], v[64:65], v[220:221] op_sel_hi:[1,0] neg_lo:[0,1] neg_hi:[0,1]
	v_pk_mul_f32 v[2:3], v[2:3], v[222:223] op_sel_hi:[1,0]
	v_pk_mul_f32 v[4:5], v[4:5], v[222:223] op_sel_hi:[1,0]
	v_pk_mul_f32 v[6:7], v[6:7], v[222:223] op_sel_hi:[1,0]
	v_pk_mul_f32 v[8:9], v[8:9], v[222:223] op_sel_hi:[1,0]
	v_pk_mul_f32 v[10:11], v[10:11], v[222:223] op_sel_hi:[1,0]
	v_pk_mul_f32 v[12:13], v[12:13], v[222:223] op_sel_hi:[1,0]
	v_pk_mul_f32 v[14:15], v[14:15], v[222:223] op_sel_hi:[1,0]
	v_pk_mul_f32 v[16:17], v[16:17], v[222:223] op_sel_hi:[1,0]
	v_pk_mul_f32 v[18:19], v[18:19], v[222:223] op_sel_hi:[1,0]
	v_pk_mul_f32 v[20:21], v[20:21], v[222:223] op_sel_hi:[1,0]
	v_pk_mul_f32 v[22:23], v[22:23], v[222:223] op_sel_hi:[1,0]
	v_pk_mul_f32 v[24:25], v[24:25], v[222:223] op_sel_hi:[1,0]
	v_pk_mul_f32 v[26:27], v[26:27], v[222:223] op_sel_hi:[1,0]
	v_pk_mul_f32 v[28:29], v[28:29], v[222:223] op_sel_hi:[1,0]
	v_pk_mul_f32 v[30:31], v[30:31], v[222:223] op_sel_hi:[1,0]
	v_pk_mul_f32 v[32:33], v[32:33], v[222:223] op_sel_hi:[1,0]
	v_mul_f32_e32 v160, v160, v222
	v_xor_b32_e32 v82, 0x80000000, v239
	v_mov_b32_e32 v83, v82
	v_mov_b32_e32 v84, v82
	v_mov_b32_e32 v85, v82
	v_mov_b32_e32 v86, v82
	v_mov_b32_e32 v87, v82
	v_mov_b32_e32 v88, v82
	v_mov_b32_e32 v89, v82
	v_mov_b32_e32 v90, v82
	v_mov_b32_e32 v91, v82
	v_mov_b32_e32 v92, v82
	v_mov_b32_e32 v93, v82
	v_mov_b32_e32 v94, v82
	v_mov_b32_e32 v95, v82
	v_mov_b32_e32 v96, v82
	v_mov_b32_e32 v97, v82
	s_nop 1
.LmlaSA_common:
	s_waitcnt lgkmcnt(4)
	v_mfma_f32_32x32x16_bf16 v[98:113], v[172:175], v[150:153], v[82:97]
	ds_read_b128 v[192:195], v164 offset:4608
	v_exp_f32_e32 v66, v66
	v_exp_f32_e32 v67, v67
	v_exp_f32_e32 v68, v68
	s_waitcnt lgkmcnt(4)
	v_mfma_f32_32x32x16_bf16 v[114:129], v[176:179], v[150:153], v[82:97]
	ds_read_b128 v[240:243], v164 offset:6144
	v_exp_f32_e32 v69, v69
	v_exp_f32_e32 v70, v70
	v_exp_f32_e32 v71, v71
	s_waitcnt lgkmcnt(4)
	v_mfma_f32_32x32x16_bf16 v[98:113], v[180:183], v[146:149], v[98:113]
	ds_read_b128 v[244:247], v164 offset:6656
	v_exp_f32_e32 v72, v72
	v_exp_f32_e32 v73, v73
	v_cvt_pk_bf16_f32 v34, v66, v67
	v_cvt_pk_bf16_f32 v35, v68, v69
	s_waitcnt lgkmcnt(4)
	v_mfma_f32_32x32x16_bf16 v[114:129], v[184:187], v[146:149], v[114:129]
	ds_read_b128 v[248:251], v164 offset:8192
	v_exp_f32_e32 v74, v74
	v_exp_f32_e32 v75, v75
	v_cvt_pk_bf16_f32 v36, v70, v71
	v_cvt_pk_bf16_f32 v37, v72, v73
	s_waitcnt lgkmcnt(4)
	v_mfma_f32_32x32x16_bf16 v[98:113], v[188:191], v[142:145], v[98:113]
	ds_read_b128 v[172:175], v164 offset:8704
	v_exp_f32_e32 v76, v76
	v_exp_f32_e32 v77, v77
	v_exp_f32_e32 v78, v78
	s_waitcnt lgkmcnt(4)
	v_mfma_f32_32x32x16_bf16 v[114:129], v[192:195], v[142:145], v[114:129]
	ds_read_b128 v[176:179], v164 offset:10240
	v_exp_f32_e32 v79, v79
	v_exp_f32_e32 v80, v80
	v_exp_f32_e32 v81, v81
	s_waitcnt lgkmcnt(4)
	v_mfma_f32_32x32x16_bf16 v[98:113], v[240:243], v[138:141], v[98:113]
	ds_read_b128 v[180:183], v164 offset:10752
	v_exp_f32_e32 v50, v50
	v_exp_f32_e32 v51, v51
	v_cvt_pk_bf16_f32 v38, v74, v75
	v_cvt_pk_bf16_f32 v39, v76, v77
	s_waitcnt lgkmcnt(4)
	v_mfma_f32_32x32x16_bf16 v[114:129], v[244:247], v[138:141], v[114:129]
	ds_read_b128 v[184:187], v165 offset:12288
	v_exp_f32_e32 v52, v52
	v_exp_f32_e32 v53, v53
	v_cvt_pk_bf16_f32 v40, v78, v79
	v_cvt_pk_bf16_f32 v41, v80, v81
	s_waitcnt lgkmcnt(4)
	v_mfma_f32_32x32x16_bf16 v[98:113], v[248:251], v[134:137], v[98:113]
	ds_read_b128 v[188:191], v165 offset:12800
	v_exp_f32_e32 v54, v54
	v_exp_f32_e32 v55, v55
	v_exp_f32_e32 v56, v56
	s_waitcnt lgkmcnt(4)
	v_mfma_f32_32x32x16_bf16 v[114:129], v[172:175], v[134:137], v[114:129]
	ds_read_b128 v[192:195], v165 offset:14336
	v_exp_f32_e32 v57, v57
	v_exp_f32_e32 v58, v58
	v_cvt_pk_bf16_f32 v42, v50, v51
	v_cvt_pk_bf16_f32 v43, v52, v53
	s_waitcnt lgkmcnt(4)
	v_mfma_f32_32x32x16_bf16 v[98:113], v[176:179], v[130:133], v[98:113]
	ds_read_b128 v[240:243], v165 offset:14848
	v_exp_f32_e32 v59, v59
	v_exp_f32_e32 v60, v60
	v_cvt_pk_bf16_f32 v44, v54, v55
	v_cvt_pk_bf16_f32 v45, v56, v57
	s_waitcnt lgkmcnt(4)
	v_mfma_f32_32x32x16_bf16 v[114:129], v[180:183], v[130:133], v[114:129]
	ds_read_b128 v[244:247], v165 offset:16384
	v_exp_f32_e32 v61, v61
	v_exp_f32_e32 v62, v62
	v_exp_f32_e32 v63, v63
	s_waitcnt lgkmcnt(4)
	v_mfma_f32_32x32x16_bf16 v[2:17], v[184:187], v[34:37], v[2:17]
	ds_read_b128 v[248:251], v165 offset:16896
	v_exp_f32_e32 v64, v64
	v_exp_f32_e32 v65, v65
	v_cvt_pk_bf16_f32 v46, v58, v59
	v_cvt_pk_bf16_f32 v47, v60, v61
	s_waitcnt lgkmcnt(4)
	v_mfma_f32_32x32x16_bf16 v[18:33], v[188:191], v[34:37], v[18:33]
	ds_read_b128 v[172:175], v165 offset:18432
	v_cvt_pk_bf16_f32 v48, v62, v63
	v_cvt_pk_bf16_f32 v49, v64, v65
	v_add_f32_e32 v166, v66, v67
	v_add_f32_e32 v167, v68, v69
	v_add_f32_e32 v168, v70, v71
	v_add_f32_e32 v169, v72, v73
	s_waitcnt lgkmcnt(4)
	v_mfma_f32_32x32x16_bf16 v[2:17], v[192:195], v[38:41], v[2:17]
	ds_read_b128 v[176:179], v165 offset:18944
	v_add_f32_e32 v166, v166, v74
	v_add_f32_e32 v167, v167, v75
	v_add_f32_e32 v168, v168, v76
	v_add_f32_e32 v169, v169, v77
	v_max3_f32 v162, v98, v99, v100
	v_max3_f32 v163, v114, v115, v116
	s_waitcnt lgkmcnt(4)
	v_mfma_f32_32x32x16_bf16 v[18:33], v[240:243], v[38:41], v[18:33]
	v_add_f32_e32 v166, v166, v78
	v_add_f32_e32 v167, v167, v79
	v_add_f32_e32 v168, v168, v80
	v_add_f32_e32 v169, v169, v81
	v_max3_f32 v162, v162, v101, v102
	v_max3_f32 v163, v163, v117, v118
	s_waitcnt lgkmcnt(3)
	v_mfma_f32_32x32x16_bf16 v[2:17], v[244:247], v[42:45], v[2:17]
	v_add_f32_e32 v166, v166, v50
	v_add_f32_e32 v167, v167, v51
	v_add_f32_e32 v168, v168, v52
	v_add_f32_e32 v169, v169, v53
	v_max3_f32 v162, v162, v103, v104
	v_max3_f32 v163, v163, v119, v120
	s_waitcnt lgkmcnt(2)
	v_mfma_f32_32x32x16_bf16 v[18:33], v[248:251], v[42:45], v[18:33]
	v_add_f32_e32 v166, v166, v54
	v_add_f32_e32 v167, v167, v55
	v_add_f32_e32 v168, v168, v56
	v_add_f32_e32 v169, v169, v57
	v_max3_f32 v162, v162, v105, v106
	v_max3_f32 v163, v163, v121, v122
	s_waitcnt lgkmcnt(1)
	v_mfma_f32_32x32x16_bf16 v[2:17], v[172:175], v[46:49], v[2:17]
	v_add_f32_e32 v166, v166, v58
	v_add_f32_e32 v167, v167, v59
	v_add_f32_e32 v168, v168, v60
	v_add_f32_e32 v169, v169, v61
	v_max3_f32 v162, v162, v107, v108
	v_max3_f32 v163, v163, v123, v124
	s_waitcnt lgkmcnt(0)
	v_mfma_f32_32x32x16_bf16 v[18:33], v[176:179], v[46:49], v[18:33]
	v_add_f32_e32 v166, v166, v62
	v_add_f32_e32 v167, v167, v63
	v_add_f32_e32 v168, v168, v64
	v_add_f32_e32 v169, v169, v65
	v_max3_f32 v162, v162, v109, v110
	v_max3_f32 v163, v163, v125, v126
	v_max3_f32 v162, v162, v111, v112
	v_max3_f32 v163, v163, v127, v128
	v_add_f32_e32 v166, v166, v167
	v_add_f32_e32 v168, v168, v169
	v_add_f32_e32 v166, v166, v168
	v_add_f32_e32 v160, v160, v166
	v_max3_f32 v162, v162, v113, v129
	v_max_f32_e32 v162, v162, v163
	s_andn2_b64 vcc, exec, s[16:17]
	s_cbranch_vccnz .LmlaSA_w2
	s_waitcnt vmcnt(3)
	s_branch .LmlaSA_wd

.LmlaSA_wd:
	s_barrier
	v_add_u32_e32 v164, s20, v238
	v_add_u32_e32 v165, s19, v238
	ds_read_b128 v[172:175], v164
	ds_read_b128 v[176:179], v164 offset:512
	ds_read_b128 v[180:183], v164 offset:2048
	ds_read_b128 v[184:187], v164 offset:2560
	ds_read_b128 v[188:191], v164 offset:4096
	s_mov_b64 s[6:7], 0x16040000
	s_add_i32 s24, s18, s4
	v_lshl_add_u64 v[218:219], v[154:155], 0, s[6:7]
	s_mov_b32 m0, s24
	s_mov_b64 s[6:7], 0x18000200
	global_load_lds_dwordx4 v[218:219], off
	v_lshl_add_u64 v[218:219], v[156:157], 0, s[6:7]
	s_add_i32 m0, s24, 0x3000
	s_andn2_b64 vcc, exec, s[16:17]
	global_load_lds_dwordx4 v[218:219], off
	s_cbranch_vccnz .LmlaSB_nokr
	s_mov_b64 s[6:7], 0x7840300
	v_lshl_add_u64 v[218:219], v[158:159], 0, s[6:7]
	s_add_i32 m0, s24, 0x2000
	s_nop 0
	global_load_lds_dwordx4 v[218:219], off
.LmlaSB_nokr:
	v_cmp_lt_f32_e32 vcc, s33, v162
	s_cbranch_vccz .LmlaSB_common
	v_mov_b32_e32 v163, v162
	s_nop 1
	v_permlane32_swap_b32_e32 v162, v163
	v_max_f32_e32 v162, v162, v163
	v_max_f32_e32 v220, 0, v162
	v_exp_f32_e64 v222, -v220
	v_add_f32_e32 v239, v239, v220
	v_pk_add_f32 v[98:99], v[98:99], v[220:221] op_sel_hi:[1,0] neg_lo:[0,1] neg_hi:[0,1]
	v_pk_add_f32 v[100:101], v[100:101], v[220:221] op_sel_hi:[1,0] neg_lo:[0,1] neg_hi:[0,1]
	v_pk_add_f32 v[102:103], v[102:103], v[220:221] op_sel_hi:[1,0] neg_lo:[0,1] neg_hi:[0,1]
	v_pk_add_f32 v[104:105], v[104:105], v[220:221] op_sel_hi:[1,0] neg_lo:[0,1] neg_hi:[0,1]
	v_pk_add_f32 v[106:107], v[106:107], v[220:221] op_sel_hi:[1,0] neg_lo:[0,1] neg_hi:[0,1]
	v_pk_add_f32 v[108:109], v[108:109], v[220:221] op_sel_hi:[1,0] neg_lo:[0,1] neg_hi:[0,1]
	v_pk_add_f32 v[110:111], v[110:111], v[220:221] op_sel_hi:[1,0] neg_lo:[0,1] neg_hi:[0,1]
	v_pk_add_f32 v[112:113], v[112:113], v[220:221] op_sel_hi:[1,0] neg_lo:[0,1] neg_hi:[0,1]
	v_pk_add_f32 v[114:115], v[114:115], v[220:221] op_sel_hi:[1,0] neg_lo:[0,1] neg_hi:[0,1]
	v_pk_add_f32 v[116:117], v[116:117], v[220:221] op_sel_hi:[1,0] neg_lo:[0,1] neg_hi:[0,1]
	v_pk_add_f32 v[118:119], v[118:119], v[220:221] op_sel_hi:[1,0] neg_lo:[0,1] neg_hi:[0,1]
	v_pk_add_f32 v[120:121], v[120:121], v[220:221] op_sel_hi:[1,0] neg_lo:[0,1] neg_hi:[0,1]
	v_pk_add_f32 v[122:123], v[122:123], v[220:221] op_sel_hi:[1,0] neg_lo:[0,1] neg_hi:[0,1]
	v_pk_add_f32 v[124:125], v[124:125], v[220:221] op_sel_hi:[1,0] neg_lo:[0,1] neg_hi:[0,1]
	v_pk_add_f32 v[126:127], v[126:127], v[220:221] op_sel_hi:[1,0] neg_lo:[0,1] neg_hi:[0,1]
	v_pk_add_f32 v[128:129], v[128:129], v[220:221] op_sel_hi:[1,0] neg_lo:[0,1] neg_hi:[0,1]
	v_pk_mul_f32 v[2:3], v[2:3], v[222:223] op_sel_hi:[1,0]
	v_pk_mul_f32 v[4:5], v[4:5], v[222:223] op_sel_hi:[1,0]
	v_pk_mul_f32 v[6:7], v[6:7], v[222:223] op_sel_hi:[1,0]
	v_pk_mul_f32 v[8:9], v[8:9], v[222:223] op_sel_hi:[1,0]
	v_pk_mul_f32 v[10:11], v[10:11], v[222:223] op_sel_hi:[1,0]
	v_pk_mul_f32 v[12:13], v[12:13], v[222:223] op_sel_hi:[1,0]
	v_pk_mul_f32 v[14:15], v[14:15], v[222:223] op_sel_hi:[1,0]
	v_pk_mul_f32 v[16:17], v[16:17], v[222:223] op_sel_hi:[1,0]
	v_pk_mul_f32 v[18:19], v[18:19], v[222:223] op_sel_hi:[1,0]
	v_pk_mul_f32 v[20:21], v[20:21], v[222:223] op_sel_hi:[1,0]
	v_pk_mul_f32 v[22:23], v[22:23], v[222:223] op_sel_hi:[1,0]
	v_pk_mul_f32 v[24:25], v[24:25], v[222:223] op_sel_hi:[1,0]
	v_pk_mul_f32 v[26:27], v[26:27], v[222:223] op_sel_hi:[1,0]
	v_pk_mul_f32 v[28:29], v[28:29], v[222:223] op_sel_hi:[1,0]
	v_pk_mul_f32 v[30:31], v[30:31], v[222:223] op_sel_hi:[1,0]
	v_pk_mul_f32 v[32:33], v[32:33], v[222:223] op_sel_hi:[1,0]
	v_mul_f32_e32 v160, v160, v222
	v_xor_b32_e32 v82, 0x80000000, v239
	v_mov_b32_e32 v83, v82
	v_mov_b32_e32 v84, v82
	v_mov_b32_e32 v85, v82
	v_mov_b32_e32 v86, v82
	v_mov_b32_e32 v87, v82
	v_mov_b32_e32 v88, v82
	v_mov_b32_e32 v89, v82
	v_mov_b32_e32 v90, v82
	v_mov_b32_e32 v91, v82
	v_mov_b32_e32 v92, v82
	v_mov_b32_e32 v93, v82
	v_mov_b32_e32 v94, v82
	v_mov_b32_e32 v95, v82
	v_mov_b32_e32 v96, v82
	v_mov_b32_e32 v97, v82
	s_nop 1
; template <bool SWA> ...
;     ...
;     int t = 0;
;     if (wv >= 4) __builtin_amdgcn_s_setprio(1);
;     for (; t < ntiles - 2; t += 2) { AT_STEP(t, sA0, sA1, sB0, sB1, true); AT_STEP(t + 1, sB0, sB1, sA0, sA1, true); }
.LmlaSB_common:
	s_waitcnt lgkmcnt(4)
	v_mfma_f32_32x32x16_bf16 v[66:81], v[172:175], v[150:153], v[82:97]
	ds_read_b128 v[192:195], v164 offset:4608
	v_exp_f32_e32 v98, v98
	v_exp_f32_e32 v99, v99
	v_exp_f32_e32 v100, v100
	s_waitcnt lgkmcnt(4)
	v_mfma_f32_32x32x16_bf16 v[50:65], v[176:179], v[150:153], v[82:97]
	ds_read_b128 v[240:243], v164 offset:6144
	v_exp_f32_e32 v101, v101
	v_exp_f32_e32 v102, v102
	v_exp_f32_e32 v103, v103
	s_waitcnt lgkmcnt(4)
	v_mfma_f32_32x32x16_bf16 v[66:81], v[180:183], v[146:149], v[66:81]
	ds_read_b128 v[244:247], v164 offset:6656
	v_exp_f32_e32 v104, v104
	v_exp_f32_e32 v105, v105
	v_cvt_pk_bf16_f32 v34, v98, v99
	v_cvt_pk_bf16_f32 v35, v100, v101
	s_waitcnt lgkmcnt(4)
	v_mfma_f32_32x32x16_bf16 v[50:65], v[184:187], v[146:149], v[50:65]
	ds_read_b128 v[248:251], v164 offset:8192
	v_exp_f32_e32 v106, v106
	v_exp_f32_e32 v107, v107
	v_cvt_pk_bf16_f32 v36, v102, v103
	v_cvt_pk_bf16_f32 v37, v104, v105
	s_waitcnt lgkmcnt(4)
	v_mfma_f32_32x32x16_bf16 v[66:81], v[188:191], v[142:145], v[66:81]
	ds_read_b128 v[172:175], v164 offset:8704
	v_exp_f32_e32 v108, v108
	v_exp_f32_e32 v109, v109
	v_exp_f32_e32 v110, v110
	s_waitcnt lgkmcnt(4)
	v_mfma_f32_32x32x16_bf16 v[50:65], v[192:195], v[142:145], v[50:65]
	ds_read_b128 v[176:179], v164 offset:10240
	v_exp_f32_e32 v111, v111
	v_exp_f32_e32 v112, v112
	v_exp_f32_e32 v113, v113
	s_waitcnt lgkmcnt(4)
	v_mfma_f32_32x32x16_bf16 v[66:81], v[240:243], v[138:141], v[66:81]
	ds_read_b128 v[180:183], v164 offset:10752
	v_exp_f32_e32 v114, v114
	v_exp_f32_e32 v115, v115
	v_cvt_pk_bf16_f32 v38, v106, v107
	v_cvt_pk_bf16_f32 v39, v108, v109
	s_waitcnt lgkmcnt(4)
	v_mfma_f32_32x32x16_bf16 v[50:65], v[244:247], v[138:141], v[50:65]
	ds_read_b128 v[184:187], v165 offset:12288
	v_exp_f32_e32 v116, v116
	v_exp_f32_e32 v117, v117
	v_cvt_pk_bf16_f32 v40, v110, v111
	v_cvt_pk_bf16_f32 v41, v112, v113
	s_waitcnt lgkmcnt(4)
	v_mfma_f32_32x32x16_bf16 v[66:81], v[248:251], v[134:137], v[66:81]
	ds_read_b128 v[188:191], v165 offset:12800
	v_exp_f32_e32 v118, v118
	v_exp_f32_e32 v119, v119
	v_exp_f32_e32 v120, v120
	s_waitcnt lgkmcnt(4)
	v_mfma_f32_32x32x16_bf16 v[50:65], v[172:175], v[134:137], v[50:65]
	ds_read_b128 v[192:195], v165 offset:14336
	v_exp_f32_e32 v121, v121
	v_exp_f32_e32 v122, v122
	v_cvt_pk_bf16_f32 v42, v114, v115
	v_cvt_pk_bf16_f32 v43, v116, v117
	s_waitcnt lgkmcnt(4)
	v_mfma_f32_32x32x16_bf16 v[66:81], v[176:179], v[130:133], v[66:81]
	ds_read_b128 v[240:243], v165 offset:14848
	v_exp_f32_e32 v123, v123
	v_exp_f32_e32 v124, v124
	v_cvt_pk_bf16_f32 v44, v118, v119
	v_cvt_pk_bf16_f32 v45, v120, v121
	s_waitcnt lgkmcnt(4)
	v_mfma_f32_32x32x16_bf16 v[50:65], v[180:183], v[130:133], v[50:65]
	ds_read_b128 v[244:247], v165 offset:16384
	v_exp_f32_e32 v125, v125
	v_exp_f32_e32 v126, v126
	v_exp_f32_e32 v127, v127
	s_waitcnt lgkmcnt(4)
	v_mfma_f32_32x32x16_bf16 v[2:17], v[184:187], v[34:37], v[2:17]
	ds_read_b128 v[248:251], v165 offset:16896
	v_exp_f32_e32 v128, v128
	v_exp_f32_e32 v129, v129
	v_cvt_pk_bf16_f32 v46, v122, v123
	v_cvt_pk_bf16_f32 v47, v124, v125
	s_waitcnt lgkmcnt(4)
	v_mfma_f32_32x32x16_bf16 v[18:33], v[188:191], v[34:37], v[18:33]
	ds_read_b128 v[172:175], v165 offset:18432
	v_cvt_pk_bf16_f32 v48, v126, v127
	v_cvt_pk_bf16_f32 v49, v128, v129
	v_add_f32_e32 v166, v98, v99
	v_add_f32_e32 v167, v100, v101
	v_add_f32_e32 v168, v102, v103
	v_add_f32_e32 v169, v104, v105
	s_waitcnt lgkmcnt(4)
	v_mfma_f32_32x32x16_bf16 v[2:17], v[192:195], v[38:41], v[2:17]
	ds_read_b128 v[176:179], v165 offset:18944
	v_add_f32_e32 v166, v166, v106
	v_add_f32_e32 v167, v167, v107
	v_add_f32_e32 v168, v168, v108
	v_add_f32_e32 v169, v169, v109
	v_max3_f32 v162, v66, v67, v68
	v_max3_f32 v163, v50, v51, v52
	s_waitcnt lgkmcnt(4)
	v_mfma_f32_32x32x16_bf16 v[18:33], v[240:243], v[38:41], v[18:33]
	v_add_f32_e32 v166, v166, v110
	v_add_f32_e32 v167, v167, v111
	v_add_f32_e32 v168, v168, v112
	v_add_f32_e32 v169, v169, v113
	v_max3_f32 v162, v162, v69, v70
	v_max3_f32 v163, v163, v53, v54
	s_waitcnt lgkmcnt(3)
	v_mfma_f32_32x32x16_bf16 v[2:17], v[244:247], v[42:45], v[2:17]
	v_add_f32_e32 v166, v166, v114
	v_add_f32_e32 v167, v167, v115
	v_add_f32_e32 v168, v168, v116
	v_add_f32_e32 v169, v169, v117
	v_max3_f32 v162, v162, v71, v72
	v_max3_f32 v163, v163, v55, v56
	s_waitcnt lgkmcnt(2)
	v_mfma_f32_32x32x16_bf16 v[18:33], v[248:251], v[42:45], v[18:33]
	v_add_f32_e32 v166, v166, v118
	v_add_f32_e32 v167, v167, v119
	v_add_f32_e32 v168, v168, v120
	v_add_f32_e32 v169, v169, v121
	v_max3_f32 v162, v162, v73, v74
	v_max3_f32 v163, v163, v57, v58
	s_waitcnt lgkmcnt(1)
	v_mfma_f32_32x32x16_bf16 v[2:17], v[172:175], v[46:49], v[2:17]
	v_add_f32_e32 v166, v166, v122
	v_add_f32_e32 v167, v167, v123
	v_add_f32_e32 v168, v168, v124
	v_add_f32_e32 v169, v169, v125
	v_max3_f32 v162, v162, v75, v76
	v_max3_f32 v163, v163, v59, v60
	s_waitcnt lgkmcnt(0)
	v_mfma_f32_32x32x16_bf16 v[18:33], v[176:179], v[46:49], v[18:33]
	v_add_f32_e32 v166, v166, v126
	v_add_f32_e32 v167, v167, v127
	v_add_f32_e32 v168, v168, v128
	v_add_f32_e32 v169, v169, v129
	v_max3_f32 v162, v162, v77, v78
	v_max3_f32 v163, v163, v61, v62
	v_max3_f32 v162, v162, v79, v80
	v_max3_f32 v163, v163, v63, v64
	v_add_f32_e32 v166, v166, v167
	v_add_f32_e32 v168, v168, v169
	v_add_f32_e32 v166, v166, v168
	v_add_f32_e32 v160, v160, v166
	v_max3_f32 v162, v162, v81, v65
	v_max_f32_e32 v162, v162, v163
	s_add_i32 s21, s21, 2
	v_lshl_add_u64 v[206:207], v[206:207], 0, s[34:35]
	v_lshl_add_u64 v[208:209], v[208:209], 0, s[34:35]
	v_lshl_add_u64 v[210:211], v[210:211], 0, s[28:29]
	s_andn2_b64 vcc, exec, s[16:17]
	s_cbranch_vccnz .LmlaSB_w2
	s_waitcnt vmcnt(3)
	s_branch .LmlaSB_wd

; template <bool SWA> ...
;     ...
;     int t = 0;
;     if (wv >= 4) __builtin_amdgcn_s_setprio(1);
;     for (; t < ntiles - 2; t += 2) { AT_STEP(t, sA0, sA1, sB0, sB1, true); AT_STEP(t + 1, sB0, sB1, sA0, sA1, true); }
;     AT_STEP(t, sA0, sA1, sB0, sB1, true);
;     AT_STEP(t + 1, sB0, sB1, sA0, sA1, false);
.LmlaSB_wd:
	s_barrier
	s_cmp_lt_u32 s21, 60
	s_cbranch_scc0 .LmlaS_exit
	s_mov_b32 s5, s4
	s_mov_b32 s4, s20
	s_mov_b32 s20, s5
	s_mov_b32 s5, s19
	s_mov_b32 s19, s23
	s_mov_b32 s23, s5
	s_branch .LmlaS_top
.LmlaS_exit:
	v_add_u32_e32 v171, 0xf000, v238
	s_mov_b32 s14, 0xa000
	v_mov_b64_e32 v[34:35], v[82:83]
	v_mov_b64_e32 v[36:37], v[84:85]
	v_mov_b64_e32 v[38:39], v[86:87]
	v_mov_b64_e32 v[40:41], v[88:89]
	v_mov_b64_e32 v[42:43], v[90:91]
	v_mov_b64_e32 v[44:45], v[92:93]
	v_mov_b64_e32 v[46:47], v[94:95]
	v_mov_b64_e32 v[48:49], v[96:97]

; template <bool SWA> ...
;     ...
;     int t = 0;
;     if (wv >= 4) __builtin_amdgcn_s_setprio(1);
;     for (; t < ntiles - 2; t += 2) { AT_STEP(t, sA0, sA1, sB0, sB1, true); AT_STEP(t + 1, sB0, sB1, sA0, sA1, true); }
;     AT_STEP(t, sA0, sA1, sB0, sB1, true);
.LBB0_1048:
	ds_read_b128 v[98:101], v171
	ds_read_b128 v[108:111], v171 offset:512
	ds_read_b128 v[120:123], v171 offset:2048
	ds_read_b128 v[114:117], v171 offset:2560
	s_waitcnt lgkmcnt(3)
	v_mfma_f32_32x32x16_bf16 v[82:97], v[98:101], v[150:153], v[34:49]
	ds_read_b128 v[124:127], v171 offset:4096
	ds_read_b128 v[98:101], v171 offset:4608
	v_exp_f32_e32 v103, v66
	v_exp_f32_e32 v119, v50
	v_exp_f32_e32 v102, v67
	v_add_f32_e32 v107, v119, v103
	s_waitcnt lgkmcnt(4)
	v_mfma_f32_32x32x16_bf16 v[34:49], v[108:111], v[150:153], v[34:49]
	ds_read_b128 v[150:153], v171 offset:6144
	ds_read_b128 v[108:111], v171 offset:6656
	v_exp_f32_e32 v128, v68
	v_exp_f32_e32 v158, v52
	v_exp_f32_e32 v106, v51
	v_add_f32_e32 v113, v158, v128
	s_waitcnt lgkmcnt(4)
	v_mfma_f32_32x32x16_bf16 v[34:49], v[114:117], v[146:149], v[34:49]
	ds_read_b128 v[154:157], v171 offset:8192
	ds_read_b128 v[114:117], v171 offset:8704
	v_exp_f32_e32 v118, v69
	v_exp_f32_e32 v112, v53
	v_exp_f32_e32 v129, v70
	v_exp_f32_e32 v159, v54
	s_waitcnt lgkmcnt(4)
	v_mfma_f32_32x32x16_bf16 v[34:49], v[98:101], v[142:145], v[34:49]
	ds_read_b128 v[162:165], v171 offset:10240
	ds_read_b128 v[50:53], v171 offset:10752
	v_add_f32_e32 v99, v159, v129
	v_exp_f32_e32 v100, v71
	v_exp_f32_e32 v98, v55
	v_exp_f32_e32 v101, v72
	s_waitcnt lgkmcnt(4)
	v_mfma_f32_32x32x16_bf16 v[34:49], v[108:111], v[138:141], v[34:49]
	v_exp_f32_e32 v109, v56
	v_exp_f32_e32 v108, v73
	v_exp_f32_e32 v110, v57
	v_add_f32_e32 v111, v109, v101
	s_waitcnt lgkmcnt(2)
	v_mfma_f32_32x32x16_bf16 v[34:49], v[114:117], v[134:137], v[34:49]
	v_exp_f32_e32 v115, v74
	v_exp_f32_e32 v161, v58
	v_exp_f32_e32 v114, v75
	v_add_f32_e32 v117, v161, v115
	s_waitcnt lgkmcnt(0)
	v_mfma_f32_32x32x16_bf16 v[34:49], v[50:53], v[130:133], v[34:49]
	v_exp_f32_e32 v166, v76
	v_exp_f32_e32 v167, v60
	v_exp_f32_e32 v116, v59
	v_add_f32_e32 v105, v167, v166
	v_mfma_f32_32x32x16_bf16 v[82:97], v[120:123], v[146:149], v[82:97]
	v_exp_f32_e32 v120, v77
	v_exp_f32_e32 v104, v61
	v_exp_f32_e32 v121, v78
	v_exp_f32_e32 v146, v62
	v_mfma_f32_32x32x16_bf16 v[82:97], v[124:127], v[142:145], v[82:97]
	v_add_u32_e32 v142, s14, v237
	v_mfma_f32_32x32x16_bf16 v[82:97], v[150:153], v[138:141], v[82:97]
	v_mfma_f32_32x32x16_bf16 v[82:97], v[154:157], v[134:137], v[82:97]
	v_mfma_f32_32x32x16_bf16 v[82:97], v[162:165], v[130:133], v[82:97]
	ds_read_b128 v[130:133], v142 offset:14848
	v_exp_f32_e32 v122, v63
	v_exp_f32_e32 v141, v64
	v_cvt_pk_bf16_f32 v63, v128, v118
	v_cvt_pk_bf16_f32 v64, v129, v100
	ds_read_b128 v[126:129], v142 offset:14336
	v_add_f32_e32 v123, v146, v121
	v_exp_f32_e32 v78, v79
	ds_read_b128 v[74:77], v142 offset:12288
	ds_read_b128 v[54:57], v142 offset:12800
	v_exp_f32_e32 v79, v80
	v_exp_f32_e32 v80, v81
	v_exp_f32_e32 v124, v65
	ds_read_b128 v[66:69], v142 offset:18432
	ds_read_b128 v[50:53], v142 offset:18944
	v_add_f32_e32 v125, v141, v79
	v_cvt_pk_bf16_f32 v62, v103, v102
	ds_read_b128 v[70:73], v142 offset:16384
	ds_read_b128 v[58:61], v142 offset:16896
	v_cvt_pk_bf16_f32 v65, v101, v108
	v_cvt_pk_bf16_f32 v134, v115, v114
	v_cvt_pk_bf16_f32 v135, v166, v120
	v_cvt_pk_bf16_f32 v136, v121, v78
	s_waitcnt lgkmcnt(5)
	v_mfma_f32_32x32x16_bf16 v[2:17], v[74:77], v[62:65], v[2:17]
	v_cvt_pk_bf16_f32 v137, v79, v80
	v_cvt_pk_bf16_f32 v74, v119, v106
	v_cvt_pk_bf16_f32 v75, v158, v112
	v_cvt_pk_bf16_f32 v76, v159, v98
	v_cvt_pk_bf16_f32 v77, v109, v110
	v_cvt_pk_bf16_f32 v138, v161, v116
	v_mfma_f32_32x32x16_bf16 v[2:17], v[126:129], v[134:137], v[2:17]
	v_mov_b32_e32 v103, v1
	v_add_f32_e64 v102, v106, v102
	v_add_f32_e64 v103, v107, v103
	v_cvt_pk_bf16_f32 v139, v167, v104
	v_cvt_pk_bf16_f32 v140, v146, v122
	v_cvt_pk_bf16_f32 v141, v141, v124
	v_pk_add_f32 v[102:103], v[102:103], v[102:103] op_sel_hi:[0,1]
	s_waitcnt lgkmcnt(1)
	v_mfma_f32_32x32x16_bf16 v[2:17], v[70:73], v[74:77], v[2:17]
	v_mov_b32_e32 v119, v103
	v_add_f32_e64 v102, v112, v118
	v_add_f32_e64 v103, v113, v119
	v_add_f32_e64 v70, v102, v102
	v_add_f32_e64 v71, v102, v103
	v_mov_b32_e32 v101, v71
	v_pk_add_f32 v[70:71], v[98:99], v[100:101]
	s_nop 0
	v_pk_add_f32 v[70:71], v[70:71], v[70:71] op_sel_hi:[0,1]
	v_mfma_f32_32x32x16_bf16 v[2:17], v[66:69], v[138:141], v[2:17]
	v_mov_b32_e32 v109, v71
	v_add_f32_e64 v70, v110, v108
	v_add_f32_e64 v71, v111, v109
	v_pk_add_f32 v[70:71], v[70:71], v[70:71] op_sel_hi:[0,1]
	v_mov_b32_e32 v115, v71
	v_pk_add_f32 v[70:71], v[116:117], v[114:115]
	s_nop 0
	v_pk_add_f32 v[66:67], v[70:71], v[70:71] op_sel_hi:[0,1]
	v_mfma_f32_32x32x16_bf16 v[18:33], v[54:57], v[62:65], v[18:33]
	v_mov_b32_e32 v121, v67
	v_add_f32_e64 v66, v104, v120
	v_add_f32_e64 v67, v105, v121
	v_pk_add_f32 v[66:67], v[66:67], v[66:67] op_sel_hi:[0,1]
	v_mov_b32_e32 v79, v67
	v_pk_add_f32 v[66:67], v[122:123], v[78:79]
	s_nop 0
	v_pk_add_f32 v[66:67], v[66:67], v[66:67] op_sel_hi:[0,1]
	v_mfma_f32_32x32x16_bf16 v[18:33], v[130:133], v[134:137], v[18:33]
	v_mov_b32_e32 v81, v67
	v_add_f32_e64 v66, v124, v80
	v_add_f32_e64 v67, v125, v81
	v_add_f32_e32 v54, v66, v67
	s_waitcnt lgkmcnt(0)
	v_mfma_f32_32x32x16_bf16 v[18:33], v[58:61], v[74:77], v[18:33]
	v_mfma_f32_32x32x16_bf16 v[18:33], v[50:53], v[138:141], v[18:33]
	v_max_f32_e32 v50, v83, v83
	v_max_f32_e32 v51, v82, v82
	v_max_f32_e32 v50, v51, v50
	v_max3_f32 v51, v84, v85, v35
	v_max3_f32 v50, v50, v34, v36
	v_max3_f32 v50, v50, v37, v86
	v_max3_f32 v51, v51, v88, v89
	v_max3_f32 v50, v50, v87, v38
	v_max3_f32 v51, v51, v40, v41
	v_max3_f32 v50, v50, v39, v90
	v_max3_f32 v51, v51, v92, v93
	v_max3_f32 v50, v50, v91, v42
	v_max3_f32 v51, v51, v44, v45
	v_max3_f32 v50, v50, v43, v94
	v_max3_f32 v51, v51, v96, v97
	v_max3_f32 v50, v50, v95, v46
	v_max3_f32 v51, v51, v48, v49
	v_max3_f32 v50, v50, v47, v51
	v_mov_b32_e32 v51, v50
	s_nop 1
	v_permlane32_swap_b32_e32 v50, v51
	s_waitcnt vmcnt(0)
	v_max_f32_e32 v51, v51, v51
	v_max_f32_e32 v50, v50, v50
	v_max_f32_e32 v50, v50, v51
	v_add_f32_e32 v72, v160, v54
	v_cmp_lt_f32_e32 vcc, s33, v50
	s_barrier
; template <bool SWA> ...
;     ...
;     int t = 0;
;     if (wv >= 4) __builtin_amdgcn_s_setprio(1);
;     for (; t < ntiles - 2; t += 2) { AT_STEP(t, sA0, sA1, sB0, sB1, true); AT_STEP(t + 1, sB0, sB1, sA0, sA1, true); }
;     AT_STEP(t, sA0, sA1, sB0, sB1, true);
	s_cbranch_vccz .LBB0_1050
	v_max_f32_e32 v50, v50, v50
	v_max_f32_e32 v50, 0, v50
	v_exp_f32_e64 v52, -v50
	v_pk_add_f32 v[82:83], v[82:83], v[50:51] op_sel_hi:[1,0] neg_lo:[0,1] neg_hi:[0,1]
	v_pk_add_f32 v[34:35], v[34:35], v[50:51] op_sel_hi:[1,0] neg_lo:[0,1] neg_hi:[0,1]
	v_pk_add_f32 v[84:85], v[84:85], v[50:51] op_sel_hi:[1,0] neg_lo:[0,1] neg_hi:[0,1]
	v_pk_add_f32 v[36:37], v[36:37], v[50:51] op_sel_hi:[1,0] neg_lo:[0,1] neg_hi:[0,1]
	v_pk_add_f32 v[86:87], v[86:87], v[50:51] op_sel_hi:[1,0] neg_lo:[0,1] neg_hi:[0,1]
	v_pk_add_f32 v[38:39], v[38:39], v[50:51] op_sel_hi:[1,0] neg_lo:[0,1] neg_hi:[0,1]
	v_pk_add_f32 v[88:89], v[88:89], v[50:51] op_sel_hi:[1,0] neg_lo:[0,1] neg_hi:[0,1]
	v_pk_add_f32 v[40:41], v[40:41], v[50:51] op_sel_hi:[1,0] neg_lo:[0,1] neg_hi:[0,1]
	v_pk_add_f32 v[90:91], v[90:91], v[50:51] op_sel_hi:[1,0] neg_lo:[0,1] neg_hi:[0,1]
	v_pk_add_f32 v[42:43], v[42:43], v[50:51] op_sel_hi:[1,0] neg_lo:[0,1] neg_hi:[0,1]
	v_pk_add_f32 v[92:93], v[92:93], v[50:51] op_sel_hi:[1,0] neg_lo:[0,1] neg_hi:[0,1]
	v_pk_add_f32 v[44:45], v[44:45], v[50:51] op_sel_hi:[1,0] neg_lo:[0,1] neg_hi:[0,1]
	v_pk_add_f32 v[94:95], v[94:95], v[50:51] op_sel_hi:[1,0] neg_lo:[0,1] neg_hi:[0,1]
	v_pk_add_f32 v[46:47], v[46:47], v[50:51] op_sel_hi:[1,0] neg_lo:[0,1] neg_hi:[0,1]
	v_pk_add_f32 v[96:97], v[96:97], v[50:51] op_sel_hi:[1,0] neg_lo:[0,1] neg_hi:[0,1]
	v_pk_add_f32 v[48:49], v[48:49], v[50:51] op_sel_hi:[1,0] neg_lo:[0,1] neg_hi:[0,1]
	v_pk_mul_f32 v[16:17], v[16:17], v[52:53] op_sel_hi:[1,0]
	v_pk_mul_f32 v[14:15], v[14:15], v[52:53] op_sel_hi:[1,0]
	v_pk_mul_f32 v[12:13], v[12:13], v[52:53] op_sel_hi:[1,0]
	v_pk_mul_f32 v[10:11], v[10:11], v[52:53] op_sel_hi:[1,0]
	v_pk_mul_f32 v[8:9], v[8:9], v[52:53] op_sel_hi:[1,0]
	v_pk_mul_f32 v[6:7], v[6:7], v[52:53] op_sel_hi:[1,0]
	v_pk_mul_f32 v[4:5], v[4:5], v[52:53] op_sel_hi:[1,0]
	v_pk_mul_f32 v[2:3], v[2:3], v[52:53] op_sel_hi:[1,0]
	v_pk_mul_f32 v[32:33], v[32:33], v[52:53] op_sel_hi:[1,0]
	v_pk_mul_f32 v[30:31], v[30:31], v[52:53] op_sel_hi:[1,0]
	v_pk_mul_f32 v[28:29], v[28:29], v[52:53] op_sel_hi:[1,0]
	v_pk_mul_f32 v[26:27], v[26:27], v[52:53] op_sel_hi:[1,0]
	v_pk_mul_f32 v[24:25], v[24:25], v[52:53] op_sel_hi:[1,0]
	v_pk_mul_f32 v[22:23], v[22:23], v[52:53] op_sel_hi:[1,0]
	v_pk_mul_f32 v[20:21], v[20:21], v[52:53] op_sel_hi:[1,0]
	v_pk_mul_f32 v[18:19], v[18:19], v[52:53] op_sel_hi:[1,0]
	v_mul_f32_e32 v72, v72, v52
.LBB0_1050:
	ds_read_b128 v[66:69], v171 offset:12288
	ds_read_b128 v[78:81], v171 offset:12800
	v_exp_f32_e32 v53, v82
	v_exp_f32_e32 v52, v83
	v_exp_f32_e32 v51, v84
	v_exp_f32_e32 v50, v85
	v_exp_f32_e32 v61, v86
	v_exp_f32_e32 v64, v87
	v_exp_f32_e32 v57, v88
	v_exp_f32_e32 v60, v89
	v_cvt_pk_bf16_f32 v74, v53, v52
	v_cvt_pk_bf16_f32 v75, v51, v50
	v_cvt_pk_bf16_f32 v76, v61, v64
	v_cvt_pk_bf16_f32 v77, v57, v60
	v_exp_f32_e32 v63, v90
	v_exp_f32_e32 v62, v91
	s_waitcnt lgkmcnt(1)
	v_mfma_f32_32x32x16_bf16 v[2:17], v[66:69], v[74:77], v[2:17]
	ds_read_b128 v[66:69], v171 offset:14336
	v_exp_f32_e32 v59, v92
	v_exp_f32_e32 v58, v93
	v_exp_f32_e32 v55, v94
	v_exp_f32_e32 v56, v95
	v_exp_f32_e32 v73, v96
	v_exp_f32_e32 v54, v97
	s_waitcnt lgkmcnt(1)
	v_mfma_f32_32x32x16_bf16 v[18:33], v[78:81], v[74:77], v[18:33]
	ds_read_b128 v[78:81], v171 offset:14848
	v_cvt_pk_bf16_f32 v74, v63, v62
	v_cvt_pk_bf16_f32 v75, v59, v58
	v_cvt_pk_bf16_f32 v76, v55, v56
	v_cvt_pk_bf16_f32 v77, v73, v54
	ds_read_b128 v[82:85], v171 offset:16384
	ds_read_b128 v[86:89], v171 offset:16896
	s_waitcnt lgkmcnt(3)
	v_mfma_f32_32x32x16_bf16 v[2:17], v[66:69], v[74:77], v[2:17]
	v_exp_f32_e32 v67, v34
	v_exp_f32_e32 v70, v35
	v_exp_f32_e32 v65, v36
	v_exp_f32_e32 v68, v37
	v_exp_f32_e32 v37, v38
	v_exp_f32_e32 v66, v39
	v_exp_f32_e32 v39, v40
	s_waitcnt lgkmcnt(2)
	v_mfma_f32_32x32x16_bf16 v[18:33], v[78:81], v[74:77], v[18:33]
	v_exp_f32_e32 v40, v41
	v_cvt_pk_bf16_f32 v76, v67, v70
	v_cvt_pk_bf16_f32 v77, v65, v68
	v_cvt_pk_bf16_f32 v78, v37, v66
	v_cvt_pk_bf16_f32 v79, v39, v40
	v_exp_f32_e32 v75, v42
	v_exp_f32_e32 v42, v43
	s_waitcnt lgkmcnt(1)
	v_mfma_f32_32x32x16_bf16 v[2:17], v[82:85], v[76:79], v[2:17]
	ds_read_b128 v[80:83], v171 offset:18432
	v_exp_f32_e32 v74, v44
	v_exp_f32_e32 v38, v45
	v_exp_f32_e32 v35, v46
	v_exp_f32_e32 v36, v47
	v_exp_f32_e32 v44, v48
	v_exp_f32_e32 v34, v49
	s_waitcnt lgkmcnt(1)
	v_mfma_f32_32x32x16_bf16 v[18:33], v[86:89], v[76:79], v[18:33]
	ds_read_b128 v[76:79], v171 offset:18944
	v_cvt_pk_bf16_f32 v46, v75, v42
	v_cvt_pk_bf16_f32 v47, v74, v38
	v_cvt_pk_bf16_f32 v48, v35, v36
	v_cvt_pk_bf16_f32 v49, v44, v34
	s_waitcnt lgkmcnt(1)
	s_nop 0
	v_mfma_f32_32x32x16_bf16 v[2:17], v[80:83], v[46:49], v[2:17]
	s_waitcnt lgkmcnt(0)
	v_mfma_f32_32x32x16_bf16 v[18:33], v[76:79], v[46:49], v[18:33]
	s_waitcnt vmcnt(0)
	s_andn2_b64 vcc, exec, s[10:11]
	s_barrier
	s_cbranch_vccnz .LBB0_1026
	s_setprio 0
	s_branch .LBB0_1026
